# saddr-form LDS-DMA in 5 GEMM k-loops: remove 16 v_lshl_add_u64 per iteration
# speedup vs baseline: 1.0033x; 1.0033x over previous
; #define PG8_STAGE(bufoff, gbase, voff) do { _Pragma("unroll") for (int _i = 0; _i < 2; ++_i) \
;         __builtin_amdgcn_global_load_lds((const unsigned*)((const char*)(gbase) + (voff)[_i]), (PG8_LAS unsigned*)(lds + (bufoff) + ldsw + _i * 8192), 16, 0, 0); } while (0)
; #define PG8_LDA(dst, b, h) do { _Pragma("unroll") for (int m = 0; m < 4; ++m) _Pragma("unroll") for (int k = 0; k < 2; ++k) dst[m][k] = *(const PG8_LAS bf16x8*)(lds + PG8_SA(b, h) + aoff + m * 2048 + k * 1024); } while (0)
; #define PG8_LDB(dst, b, h) do { _Pragma("unroll") for (int n = 0; n < 2; ++n) _Pragma("unroll") for (int k = 0; k < 2; ++k) dst[n][k] = *(const PG8_LAS bf16x8*)(lds + PG8_SB(b, h) + boff + n * 2048 + k * 1024); } while (0)
; #define PG8_MMA(ai, bj, At, Bt) do { __builtin_amdgcn_s_setprio(1); _Pragma("unroll") for (int m = 0; m < 4; ++m) _Pragma("unroll") for (int n = 0; n < 2; ++n) _Pragma("unroll") for (int k = 0; k < 2; ++k) \
;         acc[ai][bj][m][n] = __builtin_amdgcn_mfma_f32_16x16x32_bf16(Bt[n][k], At[m][k], acc[ai][bj][m][n], 0, 0, 0); __builtin_amdgcn_s_setprio(0); } while (0)
; #define PG8_WAIT_V(n) asm volatile("s_waitcnt vmcnt(" #n ")" ::: "memory")
; #define PG8_WAIT_L(n) asm volatile("s_waitcnt lgkmcnt(" #n ")" ::: "memory")
; #define PG8_BAR __builtin_amdgcn_s_barrier()
; #define PG8_SCHED __builtin_amdgcn_sched_barrier(0)
; template <class Epi, class Sched, bool ALIGN_EPI = false, bool SP2 = false>
; __device__ __forceinline__ void gemm_phase(PG8_LAS unsigned char* lds, const Gemm g, const Sched& S, const Epi& E) {
;     ...
;             PG8_LDB(B0, 0, 0); PG8_LDB(B1, 0, 1); PG8_SCHED; PG8_LDA(At, 0, 0); PG8_STAGE(PG8_SA(1, 1), a1 + hstepA, voffA);
;             PG8_WAIT_V(8); PG8_WAIT_L(0); PG8_BAR; PG8_MMA(0, 0, At, B0); PG8_MMA(0, 1, At, B1); PG8_BAR; PG8_SCHED;
;             PG8_LDA(At, 0, 1); PG8_STAGE(PG8_SB(0, 0), b2, voffB); PG8_STAGE(PG8_SB(0, 1), b2 + hstepB, voffB); PG8_STAGE(PG8_SA(0, 0), a2, voffA);
;             PG8_WAIT_V(8); PG8_WAIT_L(0); PG8_BAR; PG8_MMA(1, 0, At, B0); PG8_MMA(1, 1, At, B1); PG8_BAR; PG8_SCHED;
.LBB0_365:
	ds_read_b128 v[154:157], v169
	ds_read_b128 v[158:161], v169 offset:1024
	ds_read_b128 v[162:165], v169 offset:2048
	ds_read_b128 v[174:177], v169 offset:3072
	ds_read_b128 v[178:181], v170
	ds_read_b128 v[182:185], v170 offset:1024
	ds_read_b128 v[186:189], v170 offset:2048
	ds_read_b128 v[190:193], v170 offset:3072
	s_add_u32 s24, s60, 0xfff00080
	s_addc_u32 s25, s61, -1
	s_cmp_eq_u32 s73, 60
	s_cselect_b32 s25, s9, s25
	s_cselect_b32 s24, s10, s24
	s_cselect_b32 s67, s11, s72
	s_cselect_b32 s66, s19, s21
	s_add_i32 m0, s27, 0xc000
	ds_read_b128 v[194:197], v171
	ds_read_b128 v[198:201], v171 offset:1024
	ds_read_b128 v[202:205], v171 offset:2048
	ds_read_b128 v[206:209], v171 offset:3072
	ds_read_b128 v[210:213], v171 offset:4096
	ds_read_b128 v[214:217], v171 offset:5120
	ds_read_b128 v[218:221], v171 offset:6144
	ds_read_b128 v[222:225], v171 offset:7168
	global_load_lds_dwordx4 v146, s[60:61]
	s_add_i32 m0, s27, 0xe000
	s_nop 0
	global_load_lds_dwordx4 v148, s[60:61]
	s_waitcnt vmcnt(8)
	s_waitcnt lgkmcnt(0)
	s_barrier
	s_setprio 1
	s_waitcnt lgkmcnt(0)
	v_mfma_f32_16x16x32_bf16 v[126:129], v[154:157], v[194:197], v[126:129]
	v_mfma_f32_16x16x32_bf16 v[122:125], v[162:165], v[194:197], v[122:125]
	v_mfma_f32_16x16x32_bf16 v[110:113], v[154:157], v[202:205], v[110:113]
	v_mfma_f32_16x16x32_bf16 v[106:109], v[162:165], v[202:205], v[106:109]
	v_mfma_f32_16x16x32_bf16 v[94:97], v[154:157], v[210:213], v[94:97]
	v_mfma_f32_16x16x32_bf16 v[90:93], v[162:165], v[210:213], v[90:93]
	v_mfma_f32_16x16x32_bf16 v[78:81], v[154:157], v[218:221], v[78:81]
	v_mfma_f32_16x16x32_bf16 v[74:77], v[162:165], v[218:221], v[74:77]
	v_mfma_f32_16x16x32_bf16 v[126:129], v[158:161], v[198:201], v[126:129]
	v_mfma_f32_16x16x32_bf16 v[122:125], v[174:177], v[198:201], v[122:125]
	v_mfma_f32_16x16x32_bf16 v[110:113], v[158:161], v[206:209], v[110:113]
	v_mfma_f32_16x16x32_bf16 v[106:109], v[174:177], v[206:209], v[106:109]
	v_mfma_f32_16x16x32_bf16 v[94:97], v[158:161], v[214:217], v[94:97]
	v_mfma_f32_16x16x32_bf16 v[90:93], v[174:177], v[214:217], v[90:93]
	v_mfma_f32_16x16x32_bf16 v[78:81], v[158:161], v[222:225], v[78:81]
	v_mfma_f32_16x16x32_bf16 v[74:77], v[174:177], v[222:225], v[74:77]
	s_setprio 0
	s_setprio 1
	v_mfma_f32_16x16x32_bf16 v[118:121], v[178:181], v[194:197], v[118:121]
	v_mfma_f32_16x16x32_bf16 v[114:117], v[186:189], v[194:197], v[114:117]
	v_mfma_f32_16x16x32_bf16 v[102:105], v[178:181], v[202:205], v[102:105]
	v_mfma_f32_16x16x32_bf16 v[98:101], v[186:189], v[202:205], v[98:101]
	v_mfma_f32_16x16x32_bf16 v[86:89], v[178:181], v[210:213], v[86:89]
	v_mfma_f32_16x16x32_bf16 v[82:85], v[186:189], v[210:213], v[82:85]
	v_mfma_f32_16x16x32_bf16 v[70:73], v[178:181], v[218:221], v[70:73]
	v_mfma_f32_16x16x32_bf16 v[66:69], v[186:189], v[218:221], v[66:69]
	v_mfma_f32_16x16x32_bf16 v[118:121], v[182:185], v[198:201], v[118:121]
	v_mfma_f32_16x16x32_bf16 v[114:117], v[190:193], v[198:201], v[114:117]
	v_mfma_f32_16x16x32_bf16 v[102:105], v[182:185], v[206:209], v[102:105]
	v_mfma_f32_16x16x32_bf16 v[98:101], v[190:193], v[206:209], v[98:101]
	v_mfma_f32_16x16x32_bf16 v[86:89], v[182:185], v[214:217], v[86:89]
	v_mfma_f32_16x16x32_bf16 v[82:85], v[190:193], v[214:217], v[82:85]
	v_mfma_f32_16x16x32_bf16 v[70:73], v[182:185], v[222:225], v[70:73]
	v_mfma_f32_16x16x32_bf16 v[66:69], v[190:193], v[222:225], v[66:69]
	s_setprio 0
	s_barrier
	s_add_i32 s74, s47, s26
	s_add_u32 s98, s66, 0x80
	s_addc_u32 s99, s67, 0
	s_add_u32 s100, s24, 0x80
	s_addc_u32 s101, s25, 0
	s_mov_b32 m0, s74
	ds_read_b128 v[194:197], v171 offset:16384
	ds_read_b128 v[198:201], v171 offset:17408
	ds_read_b128 v[202:205], v171 offset:18432
	ds_read_b128 v[206:209], v171 offset:19456
	ds_read_b128 v[210:213], v171 offset:20480
	ds_read_b128 v[214:217], v171 offset:21504
	ds_read_b128 v[218:221], v171 offset:22528
	ds_read_b128 v[222:225], v171 offset:23552
	global_load_lds_dwordx4 v132, s[66:67]
	s_add_i32 m0, s74, 0x2000
	s_add_u32 s74, s66, 0x100000
	s_addc_u32 s75, s67, 0
	s_add_i32 s76, s48, s26
	global_load_lds_dwordx4 v136, s[66:67]
	s_mov_b32 m0, s76
	s_nop 0
	global_load_lds_dwordx4 v132, s[74:75]
	s_add_i32 m0, s76, 0x2000
	s_nop 0
	global_load_lds_dwordx4 v136, s[74:75]
	s_mov_b32 m0, s27
	s_nop 0
	global_load_lds_dwordx4 v130, s[24:25]
	s_mov_b32 m0, s34
	s_nop 0
	global_load_lds_dwordx4 v134, s[24:25]
	s_waitcnt vmcnt(8)
	s_waitcnt lgkmcnt(0)
	s_barrier
	s_setprio 1
	s_waitcnt lgkmcnt(0)
	v_mfma_f32_16x16x32_bf16 v[62:65], v[154:157], v[194:197], v[62:65]
	v_mfma_f32_16x16x32_bf16 v[58:61], v[162:165], v[194:197], v[58:61]
	v_mfma_f32_16x16x32_bf16 v[46:49], v[154:157], v[202:205], v[46:49]
	v_mfma_f32_16x16x32_bf16 v[42:45], v[162:165], v[202:205], v[42:45]
	v_mfma_f32_16x16x32_bf16 v[30:33], v[154:157], v[210:213], v[30:33]
	v_mfma_f32_16x16x32_bf16 v[26:29], v[162:165], v[210:213], v[26:29]
	v_mfma_f32_16x16x32_bf16 v[14:17], v[154:157], v[218:221], v[14:17]
	v_mfma_f32_16x16x32_bf16 v[10:13], v[162:165], v[218:221], v[10:13]
	v_mfma_f32_16x16x32_bf16 v[62:65], v[158:161], v[198:201], v[62:65]
	v_mfma_f32_16x16x32_bf16 v[58:61], v[174:177], v[198:201], v[58:61]
	v_mfma_f32_16x16x32_bf16 v[46:49], v[158:161], v[206:209], v[46:49]
	v_mfma_f32_16x16x32_bf16 v[42:45], v[174:177], v[206:209], v[42:45]
	v_mfma_f32_16x16x32_bf16 v[30:33], v[158:161], v[214:217], v[30:33]
	v_mfma_f32_16x16x32_bf16 v[26:29], v[174:177], v[214:217], v[26:29]
	v_mfma_f32_16x16x32_bf16 v[14:17], v[158:161], v[222:225], v[14:17]
	v_mfma_f32_16x16x32_bf16 v[10:13], v[174:177], v[222:225], v[10:13]
	s_setprio 0
	s_setprio 1
	v_mfma_f32_16x16x32_bf16 v[54:57], v[178:181], v[194:197], v[54:57]
	v_mfma_f32_16x16x32_bf16 v[50:53], v[186:189], v[194:197], v[50:53]
	v_mfma_f32_16x16x32_bf16 v[38:41], v[178:181], v[202:205], v[38:41]
	v_mfma_f32_16x16x32_bf16 v[34:37], v[186:189], v[202:205], v[34:37]
	v_mfma_f32_16x16x32_bf16 v[22:25], v[178:181], v[210:213], v[22:25]
	v_mfma_f32_16x16x32_bf16 v[18:21], v[186:189], v[210:213], v[18:21]
	v_mfma_f32_16x16x32_bf16 v[6:9], v[178:181], v[218:221], v[6:9]
	v_mfma_f32_16x16x32_bf16 v[2:5], v[186:189], v[218:221], v[2:5]
	v_mfma_f32_16x16x32_bf16 v[54:57], v[182:185], v[198:201], v[54:57]
	v_mfma_f32_16x16x32_bf16 v[50:53], v[190:193], v[198:201], v[50:53]
	v_mfma_f32_16x16x32_bf16 v[38:41], v[182:185], v[206:209], v[38:41]
	v_mfma_f32_16x16x32_bf16 v[34:37], v[190:193], v[206:209], v[34:37]
	v_mfma_f32_16x16x32_bf16 v[22:25], v[182:185], v[214:217], v[22:25]
	v_mfma_f32_16x16x32_bf16 v[18:21], v[190:193], v[214:217], v[18:21]
	v_mfma_f32_16x16x32_bf16 v[6:9], v[182:185], v[222:225], v[6:9]
	v_mfma_f32_16x16x32_bf16 v[2:5], v[190:193], v[222:225], v[2:5]
	s_setprio 0
	s_barrier
; #define PG8_STAGE(bufoff, gbase, voff) do { _Pragma("unroll") for (int _i = 0; _i < 2; ++_i) \
;         __builtin_amdgcn_global_load_lds((const unsigned*)((const char*)(gbase) + (voff)[_i]), (PG8_LAS unsigned*)(lds + (bufoff) + ldsw + _i * 8192), 16, 0, 0); } while (0)
; #define PG8_LDA(dst, b, h) do { _Pragma("unroll") for (int m = 0; m < 4; ++m) _Pragma("unroll") for (int k = 0; k < 2; ++k) dst[m][k] = *(const PG8_LAS bf16x8*)(lds + PG8_SA(b, h) + aoff + m * 2048 + k * 1024); } while (0)
; #define PG8_LDB(dst, b, h) do { _Pragma("unroll") for (int n = 0; n < 2; ++n) _Pragma("unroll") for (int k = 0; k < 2; ++k) dst[n][k] = *(const PG8_LAS bf16x8*)(lds + PG8_SB(b, h) + boff + n * 2048 + k * 1024); } while (0)
; #define PG8_MMA(ai, bj, At, Bt) do { __builtin_amdgcn_s_setprio(1); _Pragma("unroll") for (int m = 0; m < 4; ++m) _Pragma("unroll") for (int n = 0; n < 2; ++n) _Pragma("unroll") for (int k = 0; k < 2; ++k) \
;         acc[ai][bj][m][n] = __builtin_amdgcn_mfma_f32_16x16x32_bf16(Bt[n][k], At[m][k], acc[ai][bj][m][n], 0, 0, 0); __builtin_amdgcn_s_setprio(0); } while (0)
; #define PG8_WAIT_V(n) asm volatile("s_waitcnt vmcnt(" #n ")" ::: "memory")
; #define PG8_WAIT_L(n) asm volatile("s_waitcnt lgkmcnt(" #n ")" ::: "memory")
; #define PG8_BAR __builtin_amdgcn_s_barrier()
; #define PG8_SCHED __builtin_amdgcn_sched_barrier(0)
; template <class Epi, class Sched, bool ALIGN_EPI = false, bool SP2 = false>
; __device__ __forceinline__ void gemm_phase(PG8_LAS unsigned char* lds, const Gemm g, const Sched& S, const Epi& E) {
;     ...
;             PG8_LDB(B0, 1, 0); PG8_LDB(B1, 1, 1); PG8_SCHED; PG8_LDA(At, 1, 0); PG8_STAGE(PG8_SA(0, 1), a2 + hstepA, voffA);
;             PG8_WAIT_V(8); PG8_WAIT_L(0); PG8_BAR; PG8_MMA(0, 0, At, B0); PG8_MMA(0, 1, At, B1); PG8_BAR; PG8_SCHED;
;             PG8_LDA(At, 1, 1); PG8_STAGE(PG8_SB(1, 0), b3, voffB); PG8_STAGE(PG8_SB(1, 1), b3 + hstepB, voffB); PG8_STAGE(PG8_SA(1, 0), a3, voffA);
;             PG8_WAIT_V(8); PG8_WAIT_L(0); PG8_BAR; PG8_MMA(1, 0, At, B0); PG8_MMA(1, 1, At, B1); PG8_BAR; PG8_SCHED;
	s_add_i32 s74, 0, 0x18000
	v_add_u32_e32 v138, s74, v141
	s_add_i32 s75, 0, 0x1c000
	ds_read_b128 v[154:157], v138
	ds_read_b128 v[158:161], v138 offset:1024
	ds_read_b128 v[162:165], v138 offset:2048
	ds_read_b128 v[174:177], v138 offset:3072
	v_add_u32_e32 v138, s75, v141
	ds_read_b128 v[178:181], v138
	ds_read_b128 v[182:185], v138 offset:1024
	ds_read_b128 v[186:189], v138 offset:2048
	ds_read_b128 v[190:193], v138 offset:3072
	s_add_u32 s24, s24, 0x100000
	s_addc_u32 s25, s25, 0
	s_mov_b32 m0, s35
	ds_read_b128 v[194:197], v171 offset:32768
	ds_read_b128 v[198:201], v171 offset:33792
	ds_read_b128 v[202:205], v171 offset:34816
	ds_read_b128 v[206:209], v171 offset:35840
	ds_read_b128 v[210:213], v171 offset:36864
	ds_read_b128 v[214:217], v171 offset:37888
	ds_read_b128 v[218:221], v171 offset:38912
	ds_read_b128 v[222:225], v171 offset:39936
	global_load_lds_dwordx4 v130, s[24:25]
	s_mov_b32 m0, s36
	s_nop 0
	global_load_lds_dwordx4 v134, s[24:25]
	s_waitcnt vmcnt(8)
	s_waitcnt lgkmcnt(0)
	s_barrier
	s_setprio 1
	s_waitcnt lgkmcnt(0)
	v_mfma_f32_16x16x32_bf16 v[126:129], v[154:157], v[194:197], v[126:129]
	v_mfma_f32_16x16x32_bf16 v[122:125], v[162:165], v[194:197], v[122:125]
	v_mfma_f32_16x16x32_bf16 v[110:113], v[154:157], v[202:205], v[110:113]
	v_mfma_f32_16x16x32_bf16 v[106:109], v[162:165], v[202:205], v[106:109]
	v_mfma_f32_16x16x32_bf16 v[94:97], v[154:157], v[210:213], v[94:97]
	v_mfma_f32_16x16x32_bf16 v[90:93], v[162:165], v[210:213], v[90:93]
	v_mfma_f32_16x16x32_bf16 v[78:81], v[154:157], v[218:221], v[78:81]
	v_mfma_f32_16x16x32_bf16 v[74:77], v[162:165], v[218:221], v[74:77]
	v_mfma_f32_16x16x32_bf16 v[126:129], v[158:161], v[198:201], v[126:129]
	v_mfma_f32_16x16x32_bf16 v[122:125], v[174:177], v[198:201], v[122:125]
	v_mfma_f32_16x16x32_bf16 v[110:113], v[158:161], v[206:209], v[110:113]
	v_mfma_f32_16x16x32_bf16 v[106:109], v[174:177], v[206:209], v[106:109]
	v_mfma_f32_16x16x32_bf16 v[94:97], v[158:161], v[214:217], v[94:97]
	v_mfma_f32_16x16x32_bf16 v[90:93], v[174:177], v[214:217], v[90:93]
	v_mfma_f32_16x16x32_bf16 v[78:81], v[158:161], v[222:225], v[78:81]
	v_mfma_f32_16x16x32_bf16 v[74:77], v[174:177], v[222:225], v[74:77]
	s_setprio 0
	s_setprio 1
	v_mfma_f32_16x16x32_bf16 v[118:121], v[178:181], v[194:197], v[118:121]
	v_mfma_f32_16x16x32_bf16 v[114:117], v[186:189], v[194:197], v[114:117]
	v_mfma_f32_16x16x32_bf16 v[102:105], v[178:181], v[202:205], v[102:105]
	v_mfma_f32_16x16x32_bf16 v[98:101], v[186:189], v[202:205], v[98:101]
	v_mfma_f32_16x16x32_bf16 v[86:89], v[178:181], v[210:213], v[86:89]
	v_mfma_f32_16x16x32_bf16 v[82:85], v[186:189], v[210:213], v[82:85]
	v_mfma_f32_16x16x32_bf16 v[70:73], v[178:181], v[218:221], v[70:73]
	v_mfma_f32_16x16x32_bf16 v[66:69], v[186:189], v[218:221], v[66:69]
	v_mfma_f32_16x16x32_bf16 v[118:121], v[182:185], v[198:201], v[118:121]
	v_mfma_f32_16x16x32_bf16 v[114:117], v[190:193], v[198:201], v[114:117]
	v_mfma_f32_16x16x32_bf16 v[102:105], v[182:185], v[206:209], v[102:105]
	v_mfma_f32_16x16x32_bf16 v[98:101], v[190:193], v[206:209], v[98:101]
	v_mfma_f32_16x16x32_bf16 v[86:89], v[182:185], v[214:217], v[86:89]
	v_mfma_f32_16x16x32_bf16 v[82:85], v[190:193], v[214:217], v[82:85]
	v_mfma_f32_16x16x32_bf16 v[70:73], v[182:185], v[222:225], v[70:73]
	v_mfma_f32_16x16x32_bf16 v[66:69], v[190:193], v[222:225], v[66:69]
	s_setprio 0
	s_barrier
	s_add_i32 s24, s74, s26
	s_mov_b32 m0, s24
	ds_read_b128 v[194:197], v171 offset:49152
	ds_read_b128 v[198:201], v171 offset:50176
	ds_read_b128 v[202:205], v171 offset:51200
	ds_read_b128 v[206:209], v171 offset:52224
	ds_read_b128 v[210:213], v171 offset:53248
	ds_read_b128 v[214:217], v171 offset:54272
	ds_read_b128 v[218:221], v171 offset:55296
	ds_read_b128 v[222:225], v171 offset:56320
	global_load_lds_dwordx4 v132, s[98:99]
	s_add_i32 m0, s24, 0x2000
	s_add_u32 s24, s66, 0x100080
	s_addc_u32 s25, s67, 0
	s_add_i32 s66, s75, s26
	global_load_lds_dwordx4 v136, s[98:99]
	s_mov_b32 m0, s66
	s_nop 0
	global_load_lds_dwordx4 v132, s[24:25]
	s_add_i32 m0, s66, 0x2000
	s_nop 0
	global_load_lds_dwordx4 v136, s[24:25]
	s_mov_b32 m0, s42
	s_nop 0
	global_load_lds_dwordx4 v130, s[100:101]
	s_mov_b32 m0, s43
	s_nop 0
	global_load_lds_dwordx4 v134, s[100:101]
	s_waitcnt vmcnt(8)
	s_waitcnt lgkmcnt(0)
	s_barrier
	s_setprio 1
	s_waitcnt lgkmcnt(0)
	v_mfma_f32_16x16x32_bf16 v[62:65], v[154:157], v[194:197], v[62:65]
	v_mfma_f32_16x16x32_bf16 v[58:61], v[162:165], v[194:197], v[58:61]
	v_mfma_f32_16x16x32_bf16 v[46:49], v[154:157], v[202:205], v[46:49]
	v_mfma_f32_16x16x32_bf16 v[42:45], v[162:165], v[202:205], v[42:45]
	v_mfma_f32_16x16x32_bf16 v[30:33], v[154:157], v[210:213], v[30:33]
	v_mfma_f32_16x16x32_bf16 v[26:29], v[162:165], v[210:213], v[26:29]
	v_mfma_f32_16x16x32_bf16 v[14:17], v[154:157], v[218:221], v[14:17]
	v_mfma_f32_16x16x32_bf16 v[10:13], v[162:165], v[218:221], v[10:13]
	v_mfma_f32_16x16x32_bf16 v[62:65], v[158:161], v[198:201], v[62:65]
	v_mfma_f32_16x16x32_bf16 v[58:61], v[174:177], v[198:201], v[58:61]
	v_mfma_f32_16x16x32_bf16 v[46:49], v[158:161], v[206:209], v[46:49]
	v_mfma_f32_16x16x32_bf16 v[42:45], v[174:177], v[206:209], v[42:45]
	v_mfma_f32_16x16x32_bf16 v[30:33], v[158:161], v[214:217], v[30:33]
	v_mfma_f32_16x16x32_bf16 v[26:29], v[174:177], v[214:217], v[26:29]
	v_mfma_f32_16x16x32_bf16 v[14:17], v[158:161], v[222:225], v[14:17]
	v_mfma_f32_16x16x32_bf16 v[10:13], v[174:177], v[222:225], v[10:13]
	s_setprio 0
	s_setprio 1
	v_mfma_f32_16x16x32_bf16 v[54:57], v[178:181], v[194:197], v[54:57]
	v_mfma_f32_16x16x32_bf16 v[50:53], v[186:189], v[194:197], v[50:53]
	v_mfma_f32_16x16x32_bf16 v[38:41], v[178:181], v[202:205], v[38:41]
	v_mfma_f32_16x16x32_bf16 v[34:37], v[186:189], v[202:205], v[34:37]
	v_mfma_f32_16x16x32_bf16 v[22:25], v[178:181], v[210:213], v[22:25]
	v_mfma_f32_16x16x32_bf16 v[18:21], v[186:189], v[210:213], v[18:21]
	v_mfma_f32_16x16x32_bf16 v[6:9], v[178:181], v[218:221], v[6:9]
	v_mfma_f32_16x16x32_bf16 v[2:5], v[186:189], v[218:221], v[2:5]
	v_mfma_f32_16x16x32_bf16 v[54:57], v[182:185], v[198:201], v[54:57]
	v_mfma_f32_16x16x32_bf16 v[50:53], v[190:193], v[198:201], v[50:53]
	v_mfma_f32_16x16x32_bf16 v[38:41], v[182:185], v[206:209], v[38:41]
	v_mfma_f32_16x16x32_bf16 v[34:37], v[190:193], v[206:209], v[34:37]
	v_mfma_f32_16x16x32_bf16 v[22:25], v[182:185], v[214:217], v[22:25]
	v_mfma_f32_16x16x32_bf16 v[18:21], v[190:193], v[214:217], v[18:21]
	v_mfma_f32_16x16x32_bf16 v[6:9], v[182:185], v[222:225], v[6:9]
	v_mfma_f32_16x16x32_bf16 v[2:5], v[190:193], v[222:225], v[2:5]
	s_setprio 0
	s_barrier
	s_add_i32 s73, s73, 2
	s_add_u32 s60, s60, 0x100
	s_addc_u32 s61, s61, 0
	s_add_u32 s21, s21, 0x100
	s_addc_u32 s72, s72, 0
	s_cmp_gt_u32 s73, 61
	s_cbranch_scc0 .LBB0_365
	s_and_b64 vcc, exec, s[16:17]
	s_cbranch_vccz .LBB0_368
	s_barrier

; #define PG8_STAGE(bufoff, gbase, voff) do { _Pragma("unroll") for (int _i = 0; _i < 2; ++_i) \
;         __builtin_amdgcn_global_load_lds((const unsigned*)((const char*)(gbase) + (voff)[_i]), (PG8_LAS unsigned*)(lds + (bufoff) + ldsw + _i * 8192), 16, 0, 0); } while (0)
; #define PG8_LDA(dst, b, h) do { _Pragma("unroll") for (int m = 0; m < 4; ++m) _Pragma("unroll") for (int k = 0; k < 2; ++k) dst[m][k] = *(const PG8_LAS bf16x8*)(lds + PG8_SA(b, h) + aoff + m * 2048 + k * 1024); } while (0)
; #define PG8_LDB(dst, b, h) do { _Pragma("unroll") for (int n = 0; n < 2; ++n) _Pragma("unroll") for (int k = 0; k < 2; ++k) dst[n][k] = *(const PG8_LAS bf16x8*)(lds + PG8_SB(b, h) + boff + n * 2048 + k * 1024); } while (0)
; #define PG8_MMA(ai, bj, At, Bt) do { __builtin_amdgcn_s_setprio(1); _Pragma("unroll") for (int m = 0; m < 4; ++m) _Pragma("unroll") for (int n = 0; n < 2; ++n) _Pragma("unroll") for (int k = 0; k < 2; ++k) \
;         acc[ai][bj][m][n] = __builtin_amdgcn_mfma_f32_16x16x32_bf16(Bt[n][k], At[m][k], acc[ai][bj][m][n], 0, 0, 0); __builtin_amdgcn_s_setprio(0); } while (0)
; #define PG8_WAIT_V(n) asm volatile("s_waitcnt vmcnt(" #n ")" ::: "memory")
; #define PG8_WAIT_L(n) asm volatile("s_waitcnt lgkmcnt(" #n ")" ::: "memory")
; #define PG8_BAR __builtin_amdgcn_s_barrier()
; #define PG8_SCHED __builtin_amdgcn_sched_barrier(0)
; template <class Epi, class Sched, bool ALIGN_EPI = false, bool SP2 = false>
; __device__ __forceinline__ void gemm_phase(PG8_LAS unsigned char* lds, const Gemm g, const Sched& S, const Epi& E) {
;     ...
;             PG8_LDB(B0, 0, 0); PG8_LDB(B1, 0, 1); PG8_SCHED; PG8_LDA(At, 0, 0); PG8_STAGE(PG8_SA(1, 1), a1 + hstepA, voffA);
;             PG8_WAIT_V(8); PG8_WAIT_L(0); PG8_BAR; PG8_MMA(0, 0, At, B0); PG8_MMA(0, 1, At, B1); PG8_BAR; PG8_SCHED;
;             PG8_LDA(At, 0, 1); PG8_STAGE(PG8_SB(0, 0), b2, voffB); PG8_STAGE(PG8_SB(0, 1), b2 + hstepB, voffB); PG8_STAGE(PG8_SA(0, 0), a2, voffA);
;             PG8_WAIT_V(8); PG8_WAIT_L(0); PG8_BAR; PG8_MMA(1, 0, At, B0); PG8_MMA(1, 1, At, B1); PG8_BAR; PG8_SCHED;
.LBB0_839:
	ds_read_b128 v[130:133], v166
	ds_read_b128 v[134:137], v166 offset:1024
	ds_read_b128 v[138:141], v166 offset:2048
	ds_read_b128 v[142:145], v166 offset:3072
	ds_read_b128 v[170:173], v167
	ds_read_b128 v[174:177], v167 offset:1024
	ds_read_b128 v[178:181], v167 offset:2048
	ds_read_b128 v[182:185], v167 offset:3072
	s_add_u32 s24, s36, 0xfff00080
	s_addc_u32 s25, s37, -1
	s_cmp_eq_u32 s69, 60
	s_cselect_b32 s25, s17, s25
	s_cselect_b32 s24, s49, s24
	s_cselect_b32 s39, s15, s68
	s_cselect_b32 s38, s62, s63
	s_add_i32 m0, s23, 0xc000
	ds_read_b128 v[186:189], v168
	ds_read_b128 v[190:193], v168 offset:1024
	ds_read_b128 v[194:197], v168 offset:2048
	ds_read_b128 v[198:201], v168 offset:3072
	ds_read_b128 v[202:205], v168 offset:4096
	ds_read_b128 v[206:209], v168 offset:5120
	ds_read_b128 v[210:213], v168 offset:6144
	ds_read_b128 v[214:217], v168 offset:7168
	global_load_lds_dwordx4 v154, s[36:37]
	s_add_i32 m0, s23, 0xe000
	s_nop 0
	global_load_lds_dwordx4 v156, s[36:37]
	s_waitcnt vmcnt(8)
	s_waitcnt lgkmcnt(0)
	s_barrier
	s_setprio 1
	s_waitcnt lgkmcnt(0)
	v_mfma_f32_16x16x32_bf16 v[126:129], v[130:133], v[186:189], v[126:129]
	v_mfma_f32_16x16x32_bf16 v[122:125], v[138:141], v[186:189], v[122:125]
	v_mfma_f32_16x16x32_bf16 v[118:121], v[130:133], v[194:197], v[118:121]
	v_mfma_f32_16x16x32_bf16 v[114:117], v[138:141], v[194:197], v[114:117]
	v_mfma_f32_16x16x32_bf16 v[110:113], v[130:133], v[202:205], v[110:113]
	v_mfma_f32_16x16x32_bf16 v[102:105], v[138:141], v[202:205], v[102:105]
	v_mfma_f32_16x16x32_bf16 v[94:97], v[130:133], v[210:213], v[94:97]
	v_mfma_f32_16x16x32_bf16 v[86:89], v[138:141], v[210:213], v[86:89]
	v_mfma_f32_16x16x32_bf16 v[126:129], v[134:137], v[190:193], v[126:129]
	v_mfma_f32_16x16x32_bf16 v[122:125], v[142:145], v[190:193], v[122:125]
	v_mfma_f32_16x16x32_bf16 v[118:121], v[134:137], v[198:201], v[118:121]
	v_mfma_f32_16x16x32_bf16 v[114:117], v[142:145], v[198:201], v[114:117]
	v_mfma_f32_16x16x32_bf16 v[110:113], v[134:137], v[206:209], v[110:113]
	v_mfma_f32_16x16x32_bf16 v[102:105], v[142:145], v[206:209], v[102:105]
	v_mfma_f32_16x16x32_bf16 v[94:97], v[134:137], v[214:217], v[94:97]
	v_mfma_f32_16x16x32_bf16 v[86:89], v[142:145], v[214:217], v[86:89]
	s_setprio 0
	s_setprio 1
	v_mfma_f32_16x16x32_bf16 v[106:109], v[170:173], v[186:189], v[106:109]
	v_mfma_f32_16x16x32_bf16 v[98:101], v[178:181], v[186:189], v[98:101]
	v_mfma_f32_16x16x32_bf16 v[90:93], v[170:173], v[194:197], v[90:93]
	v_mfma_f32_16x16x32_bf16 v[82:85], v[178:181], v[194:197], v[82:85]
	v_mfma_f32_16x16x32_bf16 v[78:81], v[170:173], v[202:205], v[78:81]
	v_mfma_f32_16x16x32_bf16 v[74:77], v[178:181], v[202:205], v[74:77]
	v_mfma_f32_16x16x32_bf16 v[70:73], v[170:173], v[210:213], v[70:73]
	v_mfma_f32_16x16x32_bf16 v[66:69], v[178:181], v[210:213], v[66:69]
	v_mfma_f32_16x16x32_bf16 v[106:109], v[174:177], v[190:193], v[106:109]
	v_mfma_f32_16x16x32_bf16 v[98:101], v[182:185], v[190:193], v[98:101]
	v_mfma_f32_16x16x32_bf16 v[90:93], v[174:177], v[198:201], v[90:93]
	v_mfma_f32_16x16x32_bf16 v[82:85], v[182:185], v[198:201], v[82:85]
	v_mfma_f32_16x16x32_bf16 v[78:81], v[174:177], v[206:209], v[78:81]
	v_mfma_f32_16x16x32_bf16 v[74:77], v[182:185], v[206:209], v[74:77]
	v_mfma_f32_16x16x32_bf16 v[70:73], v[174:177], v[214:217], v[70:73]
	v_mfma_f32_16x16x32_bf16 v[66:69], v[182:185], v[214:217], v[66:69]
	s_setprio 0
	s_barrier
	s_add_i32 s72, s45, s26
	s_add_u32 s98, s38, 0x80
	s_addc_u32 s99, s39, 0
	s_add_u32 s100, s24, 0x80
	s_addc_u32 s101, s25, 0
	s_mov_b32 m0, s72
	ds_read_b128 v[186:189], v168 offset:16384
	ds_read_b128 v[190:193], v168 offset:17408
	ds_read_b128 v[194:197], v168 offset:18432
	ds_read_b128 v[198:201], v168 offset:19456
	ds_read_b128 v[202:205], v168 offset:20480
	ds_read_b128 v[206:209], v168 offset:21504
	ds_read_b128 v[210:213], v168 offset:22528
	ds_read_b128 v[214:217], v168 offset:23552
	global_load_lds_dwordx4 v150, s[38:39]
	s_add_i32 m0, s72, 0x2000
	s_add_u32 s72, s38, 0x100000
	s_addc_u32 s73, s39, 0
	s_add_i32 s74, s46, s26
	global_load_lds_dwordx4 v146, s[38:39]
	s_mov_b32 m0, s74
	s_nop 0
	global_load_lds_dwordx4 v150, s[72:73]
	s_add_i32 m0, s74, 0x2000
	s_nop 0
	global_load_lds_dwordx4 v146, s[72:73]
	s_mov_b32 m0, s23
	s_nop 0
	global_load_lds_dwordx4 v152, s[24:25]
	s_mov_b32 m0, s27
	s_nop 0
	global_load_lds_dwordx4 v148, s[24:25]
	s_waitcnt vmcnt(8)
	s_waitcnt lgkmcnt(0)
	s_barrier
	s_setprio 1
	s_waitcnt lgkmcnt(0)
	v_mfma_f32_16x16x32_bf16 v[62:65], v[130:133], v[186:189], v[62:65]
	v_mfma_f32_16x16x32_bf16 v[58:61], v[138:141], v[186:189], v[58:61]
	v_mfma_f32_16x16x32_bf16 v[50:53], v[130:133], v[194:197], v[50:53]
	v_mfma_f32_16x16x32_bf16 v[42:45], v[138:141], v[194:197], v[42:45]
	v_mfma_f32_16x16x32_bf16 v[34:37], v[130:133], v[202:205], v[34:37]
	v_mfma_f32_16x16x32_bf16 v[26:29], v[138:141], v[202:205], v[26:29]
	v_mfma_f32_16x16x32_bf16 v[18:21], v[130:133], v[210:213], v[18:21]
	v_mfma_f32_16x16x32_bf16 v[10:13], v[138:141], v[210:213], v[10:13]
	v_mfma_f32_16x16x32_bf16 v[62:65], v[134:137], v[190:193], v[62:65]
	v_mfma_f32_16x16x32_bf16 v[58:61], v[142:145], v[190:193], v[58:61]
	v_mfma_f32_16x16x32_bf16 v[50:53], v[134:137], v[198:201], v[50:53]
	v_mfma_f32_16x16x32_bf16 v[42:45], v[142:145], v[198:201], v[42:45]
	v_mfma_f32_16x16x32_bf16 v[34:37], v[134:137], v[206:209], v[34:37]
	v_mfma_f32_16x16x32_bf16 v[26:29], v[142:145], v[206:209], v[26:29]
	v_mfma_f32_16x16x32_bf16 v[18:21], v[134:137], v[214:217], v[18:21]
	v_mfma_f32_16x16x32_bf16 v[10:13], v[142:145], v[214:217], v[10:13]
	s_setprio 0
	s_setprio 1
	v_mfma_f32_16x16x32_bf16 v[54:57], v[170:173], v[186:189], v[54:57]
	v_mfma_f32_16x16x32_bf16 v[46:49], v[178:181], v[186:189], v[46:49]
	v_mfma_f32_16x16x32_bf16 v[38:41], v[170:173], v[194:197], v[38:41]
	v_mfma_f32_16x16x32_bf16 v[30:33], v[178:181], v[194:197], v[30:33]
	v_mfma_f32_16x16x32_bf16 v[22:25], v[170:173], v[202:205], v[22:25]
	v_mfma_f32_16x16x32_bf16 v[14:17], v[178:181], v[202:205], v[14:17]
	v_mfma_f32_16x16x32_bf16 v[6:9], v[170:173], v[210:213], v[6:9]
	v_mfma_f32_16x16x32_bf16 v[2:5], v[178:181], v[210:213], v[2:5]
	v_mfma_f32_16x16x32_bf16 v[54:57], v[174:177], v[190:193], v[54:57]
	v_mfma_f32_16x16x32_bf16 v[46:49], v[182:185], v[190:193], v[46:49]
	v_mfma_f32_16x16x32_bf16 v[38:41], v[174:177], v[198:201], v[38:41]
	v_mfma_f32_16x16x32_bf16 v[30:33], v[182:185], v[198:201], v[30:33]
	v_mfma_f32_16x16x32_bf16 v[22:25], v[174:177], v[206:209], v[22:25]
	v_mfma_f32_16x16x32_bf16 v[14:17], v[182:185], v[206:209], v[14:17]
	v_mfma_f32_16x16x32_bf16 v[6:9], v[174:177], v[214:217], v[6:9]
	v_mfma_f32_16x16x32_bf16 v[2:5], v[182:185], v[214:217], v[2:5]
	s_setprio 0
	s_barrier
; #define PG8_STAGE(bufoff, gbase, voff) do { _Pragma("unroll") for (int _i = 0; _i < 2; ++_i) \
;         __builtin_amdgcn_global_load_lds((const unsigned*)((const char*)(gbase) + (voff)[_i]), (PG8_LAS unsigned*)(lds + (bufoff) + ldsw + _i * 8192), 16, 0, 0); } while (0)
; #define PG8_LDA(dst, b, h) do { _Pragma("unroll") for (int m = 0; m < 4; ++m) _Pragma("unroll") for (int k = 0; k < 2; ++k) dst[m][k] = *(const PG8_LAS bf16x8*)(lds + PG8_SA(b, h) + aoff + m * 2048 + k * 1024); } while (0)
; #define PG8_LDB(dst, b, h) do { _Pragma("unroll") for (int n = 0; n < 2; ++n) _Pragma("unroll") for (int k = 0; k < 2; ++k) dst[n][k] = *(const PG8_LAS bf16x8*)(lds + PG8_SB(b, h) + boff + n * 2048 + k * 1024); } while (0)
; #define PG8_MMA(ai, bj, At, Bt) do { __builtin_amdgcn_s_setprio(1); _Pragma("unroll") for (int m = 0; m < 4; ++m) _Pragma("unroll") for (int n = 0; n < 2; ++n) _Pragma("unroll") for (int k = 0; k < 2; ++k) \
;         acc[ai][bj][m][n] = __builtin_amdgcn_mfma_f32_16x16x32_bf16(Bt[n][k], At[m][k], acc[ai][bj][m][n], 0, 0, 0); __builtin_amdgcn_s_setprio(0); } while (0)
; #define PG8_WAIT_V(n) asm volatile("s_waitcnt vmcnt(" #n ")" ::: "memory")
; #define PG8_WAIT_L(n) asm volatile("s_waitcnt lgkmcnt(" #n ")" ::: "memory")
; #define PG8_BAR __builtin_amdgcn_s_barrier()
; #define PG8_SCHED __builtin_amdgcn_sched_barrier(0)
; template <class Epi, class Sched, bool ALIGN_EPI = false, bool SP2 = false>
; __device__ __forceinline__ void gemm_phase(PG8_LAS unsigned char* lds, const Gemm g, const Sched& S, const Epi& E) {
;     ...
;             PG8_LDB(B0, 1, 0); PG8_LDB(B1, 1, 1); PG8_SCHED; PG8_LDA(At, 1, 0); PG8_STAGE(PG8_SA(0, 1), a2 + hstepA, voffA);
;             PG8_WAIT_V(8); PG8_WAIT_L(0); PG8_BAR; PG8_MMA(0, 0, At, B0); PG8_MMA(0, 1, At, B1); PG8_BAR; PG8_SCHED;
;             PG8_LDA(At, 1, 1); PG8_STAGE(PG8_SB(1, 0), b3, voffB); PG8_STAGE(PG8_SB(1, 1), b3 + hstepB, voffB); PG8_STAGE(PG8_SA(1, 0), a3, voffA);
;             PG8_WAIT_V(8); PG8_WAIT_L(0); PG8_BAR; PG8_MMA(1, 0, At, B0); PG8_MMA(1, 1, At, B1); PG8_BAR; PG8_SCHED;
	s_add_i32 s72, 0, 0x18000
	s_add_i32 s73, 0, 0x1c000
	v_add_u32_e32 v142, s72, v164
	v_add_u32_e32 v169, s73, v164
	ds_read_b128 v[130:133], v142
	ds_read_b128 v[134:137], v142 offset:1024
	ds_read_b128 v[138:141], v142 offset:2048
	ds_read_b128 v[142:145], v142 offset:3072
	ds_read_b128 v[170:173], v169
	ds_read_b128 v[174:177], v169 offset:1024
	ds_read_b128 v[178:181], v169 offset:2048
	ds_read_b128 v[182:185], v169 offset:3072
	s_add_u32 s24, s24, 0x100000
	s_addc_u32 s25, s25, 0
	s_mov_b32 m0, s34
	ds_read_b128 v[186:189], v168 offset:32768
	ds_read_b128 v[190:193], v168 offset:33792
	ds_read_b128 v[194:197], v168 offset:34816
	ds_read_b128 v[198:201], v168 offset:35840
	ds_read_b128 v[202:205], v168 offset:36864
	ds_read_b128 v[206:209], v168 offset:37888
	ds_read_b128 v[210:213], v168 offset:38912
	ds_read_b128 v[214:217], v168 offset:39936
	global_load_lds_dwordx4 v152, s[24:25]
	s_mov_b32 m0, s35
	s_nop 0
	global_load_lds_dwordx4 v148, s[24:25]
	s_waitcnt vmcnt(8)
	s_waitcnt lgkmcnt(0)
	s_barrier
	s_setprio 1
	s_waitcnt lgkmcnt(0)
	v_mfma_f32_16x16x32_bf16 v[126:129], v[130:133], v[186:189], v[126:129]
	v_mfma_f32_16x16x32_bf16 v[122:125], v[138:141], v[186:189], v[122:125]
	v_mfma_f32_16x16x32_bf16 v[118:121], v[130:133], v[194:197], v[118:121]
	v_mfma_f32_16x16x32_bf16 v[114:117], v[138:141], v[194:197], v[114:117]
	v_mfma_f32_16x16x32_bf16 v[110:113], v[130:133], v[202:205], v[110:113]
	v_mfma_f32_16x16x32_bf16 v[102:105], v[138:141], v[202:205], v[102:105]
	v_mfma_f32_16x16x32_bf16 v[94:97], v[130:133], v[210:213], v[94:97]
	v_mfma_f32_16x16x32_bf16 v[86:89], v[138:141], v[210:213], v[86:89]
	v_mfma_f32_16x16x32_bf16 v[126:129], v[134:137], v[190:193], v[126:129]
	v_mfma_f32_16x16x32_bf16 v[122:125], v[142:145], v[190:193], v[122:125]
	v_mfma_f32_16x16x32_bf16 v[118:121], v[134:137], v[198:201], v[118:121]
	v_mfma_f32_16x16x32_bf16 v[114:117], v[142:145], v[198:201], v[114:117]
	v_mfma_f32_16x16x32_bf16 v[110:113], v[134:137], v[206:209], v[110:113]
	v_mfma_f32_16x16x32_bf16 v[102:105], v[142:145], v[206:209], v[102:105]
	v_mfma_f32_16x16x32_bf16 v[94:97], v[134:137], v[214:217], v[94:97]
	v_mfma_f32_16x16x32_bf16 v[86:89], v[142:145], v[214:217], v[86:89]
	s_setprio 0
	s_setprio 1
	v_mfma_f32_16x16x32_bf16 v[106:109], v[170:173], v[186:189], v[106:109]
	v_mfma_f32_16x16x32_bf16 v[98:101], v[178:181], v[186:189], v[98:101]
	v_mfma_f32_16x16x32_bf16 v[90:93], v[170:173], v[194:197], v[90:93]
	v_mfma_f32_16x16x32_bf16 v[82:85], v[178:181], v[194:197], v[82:85]
	v_mfma_f32_16x16x32_bf16 v[78:81], v[170:173], v[202:205], v[78:81]
	v_mfma_f32_16x16x32_bf16 v[74:77], v[178:181], v[202:205], v[74:77]
	v_mfma_f32_16x16x32_bf16 v[70:73], v[170:173], v[210:213], v[70:73]
	v_mfma_f32_16x16x32_bf16 v[66:69], v[178:181], v[210:213], v[66:69]
	v_mfma_f32_16x16x32_bf16 v[106:109], v[174:177], v[190:193], v[106:109]
	v_mfma_f32_16x16x32_bf16 v[98:101], v[182:185], v[190:193], v[98:101]
	v_mfma_f32_16x16x32_bf16 v[90:93], v[174:177], v[198:201], v[90:93]
	v_mfma_f32_16x16x32_bf16 v[82:85], v[182:185], v[198:201], v[82:85]
	v_mfma_f32_16x16x32_bf16 v[78:81], v[174:177], v[206:209], v[78:81]
	v_mfma_f32_16x16x32_bf16 v[74:77], v[182:185], v[206:209], v[74:77]
	v_mfma_f32_16x16x32_bf16 v[70:73], v[174:177], v[214:217], v[70:73]
	v_mfma_f32_16x16x32_bf16 v[66:69], v[182:185], v[214:217], v[66:69]
	s_setprio 0
	s_barrier
	s_add_i32 s24, s72, s26
	s_mov_b32 m0, s24
	ds_read_b128 v[186:189], v168 offset:49152
	ds_read_b128 v[190:193], v168 offset:50176
	ds_read_b128 v[194:197], v168 offset:51200
	ds_read_b128 v[198:201], v168 offset:52224
	ds_read_b128 v[202:205], v168 offset:53248
	ds_read_b128 v[206:209], v168 offset:54272
	ds_read_b128 v[210:213], v168 offset:55296
	ds_read_b128 v[214:217], v168 offset:56320
	global_load_lds_dwordx4 v150, s[98:99]
	s_add_i32 m0, s24, 0x2000
	s_add_u32 s24, s38, 0x100080
	s_addc_u32 s25, s39, 0
	s_add_i32 s38, s73, s26
	global_load_lds_dwordx4 v146, s[98:99]
	s_mov_b32 m0, s38
	s_nop 0
	global_load_lds_dwordx4 v150, s[24:25]
	s_add_i32 m0, s38, 0x2000
	s_nop 0
	global_load_lds_dwordx4 v146, s[24:25]
	s_mov_b32 m0, s43
	s_nop 0
	global_load_lds_dwordx4 v152, s[100:101]
	s_mov_b32 m0, s44
	s_nop 0
	global_load_lds_dwordx4 v148, s[100:101]
	s_waitcnt vmcnt(8)
	s_waitcnt lgkmcnt(0)
	s_barrier
	s_setprio 1
	s_waitcnt lgkmcnt(0)
	v_mfma_f32_16x16x32_bf16 v[62:65], v[130:133], v[186:189], v[62:65]
	v_mfma_f32_16x16x32_bf16 v[58:61], v[138:141], v[186:189], v[58:61]
	v_mfma_f32_16x16x32_bf16 v[50:53], v[130:133], v[194:197], v[50:53]
	v_mfma_f32_16x16x32_bf16 v[42:45], v[138:141], v[194:197], v[42:45]
	v_mfma_f32_16x16x32_bf16 v[34:37], v[130:133], v[202:205], v[34:37]
	v_mfma_f32_16x16x32_bf16 v[26:29], v[138:141], v[202:205], v[26:29]
	v_mfma_f32_16x16x32_bf16 v[18:21], v[130:133], v[210:213], v[18:21]
	v_mfma_f32_16x16x32_bf16 v[10:13], v[138:141], v[210:213], v[10:13]
	v_mfma_f32_16x16x32_bf16 v[62:65], v[134:137], v[190:193], v[62:65]
	v_mfma_f32_16x16x32_bf16 v[58:61], v[142:145], v[190:193], v[58:61]
	v_mfma_f32_16x16x32_bf16 v[50:53], v[134:137], v[198:201], v[50:53]
	v_mfma_f32_16x16x32_bf16 v[42:45], v[142:145], v[198:201], v[42:45]
	v_mfma_f32_16x16x32_bf16 v[34:37], v[134:137], v[206:209], v[34:37]
	v_mfma_f32_16x16x32_bf16 v[26:29], v[142:145], v[206:209], v[26:29]
	v_mfma_f32_16x16x32_bf16 v[18:21], v[134:137], v[214:217], v[18:21]
	v_mfma_f32_16x16x32_bf16 v[10:13], v[142:145], v[214:217], v[10:13]
	s_setprio 0
	s_setprio 1
	v_mfma_f32_16x16x32_bf16 v[54:57], v[170:173], v[186:189], v[54:57]
	v_mfma_f32_16x16x32_bf16 v[46:49], v[178:181], v[186:189], v[46:49]
	v_mfma_f32_16x16x32_bf16 v[38:41], v[170:173], v[194:197], v[38:41]
	v_mfma_f32_16x16x32_bf16 v[30:33], v[178:181], v[194:197], v[30:33]
	v_mfma_f32_16x16x32_bf16 v[22:25], v[170:173], v[202:205], v[22:25]
	v_mfma_f32_16x16x32_bf16 v[14:17], v[178:181], v[202:205], v[14:17]
	v_mfma_f32_16x16x32_bf16 v[6:9], v[170:173], v[210:213], v[6:9]
	v_mfma_f32_16x16x32_bf16 v[2:5], v[178:181], v[210:213], v[2:5]
	v_mfma_f32_16x16x32_bf16 v[54:57], v[174:177], v[190:193], v[54:57]
	v_mfma_f32_16x16x32_bf16 v[46:49], v[182:185], v[190:193], v[46:49]
	v_mfma_f32_16x16x32_bf16 v[38:41], v[174:177], v[198:201], v[38:41]
	v_mfma_f32_16x16x32_bf16 v[30:33], v[182:185], v[198:201], v[30:33]
	v_mfma_f32_16x16x32_bf16 v[22:25], v[174:177], v[206:209], v[22:25]
	v_mfma_f32_16x16x32_bf16 v[14:17], v[182:185], v[206:209], v[14:17]
	v_mfma_f32_16x16x32_bf16 v[6:9], v[174:177], v[214:217], v[6:9]
	v_mfma_f32_16x16x32_bf16 v[2:5], v[182:185], v[214:217], v[2:5]
	s_setprio 0
	s_barrier
	s_add_i32 s69, s69, 2
	s_add_u32 s36, s36, 0x100
	s_addc_u32 s37, s37, 0
	s_add_u32 s63, s63, 0x100
	s_addc_u32 s68, s68, 0
	s_cmp_gt_u32 s69, 61
	s_cbranch_scc0 .LBB0_839
	s_and_b64 vcc, exec, s[10:11]
	s_cbranch_vccz .LBB0_842
	s_barrier

; #define PG8_STAGE(bufoff, gbase, voff) do { _Pragma("unroll") for (int _i = 0; _i < 2; ++_i) \
;         __builtin_amdgcn_global_load_lds((const unsigned*)((const char*)(gbase) + (voff)[_i]), (PG8_LAS unsigned*)(lds + (bufoff) + ldsw + _i * 8192), 16, 0, 0); } while (0)
; #define PG8_LDA(dst, b, h) do { _Pragma("unroll") for (int m = 0; m < 4; ++m) _Pragma("unroll") for (int k = 0; k < 2; ++k) dst[m][k] = *(const PG8_LAS bf16x8*)(lds + PG8_SA(b, h) + aoff + m * 2048 + k * 1024); } while (0)
; #define PG8_LDB(dst, b, h) do { _Pragma("unroll") for (int n = 0; n < 2; ++n) _Pragma("unroll") for (int k = 0; k < 2; ++k) dst[n][k] = *(const PG8_LAS bf16x8*)(lds + PG8_SB(b, h) + boff + n * 2048 + k * 1024); } while (0)
; #define PG8_MMA(ai, bj, At, Bt) do { __builtin_amdgcn_s_setprio(1); _Pragma("unroll") for (int m = 0; m < 4; ++m) _Pragma("unroll") for (int n = 0; n < 2; ++n) _Pragma("unroll") for (int k = 0; k < 2; ++k) \
;         acc[ai][bj][m][n] = __builtin_amdgcn_mfma_f32_16x16x32_bf16(Bt[n][k], At[m][k], acc[ai][bj][m][n], 0, 0, 0); __builtin_amdgcn_s_setprio(0); } while (0)
; #define PG8_WAIT_V(n) asm volatile("s_waitcnt vmcnt(" #n ")" ::: "memory")
; #define PG8_WAIT_L(n) asm volatile("s_waitcnt lgkmcnt(" #n ")" ::: "memory")
; #define PG8_BAR __builtin_amdgcn_s_barrier()
; #define PG8_SCHED __builtin_amdgcn_sched_barrier(0)
; template <class Epi, class Sched, bool ALIGN_EPI = false, bool SP2 = false>
; __device__ __forceinline__ void gemm_phase(PG8_LAS unsigned char* lds, const Gemm g, const Sched& S, const Epi& E) {
;     ...
;             PG8_LDB(B0, 0, 0); PG8_LDB(B1, 0, 1); PG8_SCHED; PG8_LDA(At, 0, 0); PG8_STAGE(PG8_SA(1, 1), a1 + hstepA, voffA);
;             PG8_WAIT_V(8); PG8_WAIT_L(0); PG8_BAR; PG8_MMA(0, 0, At, B0); PG8_MMA(0, 1, At, B1); PG8_BAR; PG8_SCHED;
;             PG8_LDA(At, 0, 1); PG8_STAGE(PG8_SB(0, 0), b2, voffB); PG8_STAGE(PG8_SB(0, 1), b2 + hstepB, voffB); PG8_STAGE(PG8_SA(0, 0), a2, voffA);
;             PG8_WAIT_V(8); PG8_WAIT_L(0); PG8_BAR; PG8_MMA(1, 0, At, B0); PG8_MMA(1, 1, At, B1); PG8_BAR; PG8_SCHED;
.LBB0_990:
	ds_read_b128 v[146:149], v154
	ds_read_b128 v[158:161], v154 offset:1024
	ds_read_b128 v[162:165], v154 offset:2048
	ds_read_b128 v[166:169], v154 offset:3072
	ds_read_b128 v[170:173], v155
	ds_read_b128 v[174:177], v155 offset:1024
	ds_read_b128 v[178:181], v155 offset:2048
	ds_read_b128 v[182:185], v155 offset:3072
	s_add_u32 s34, s40, 0xfff00080
	s_addc_u32 s35, s41, -1
	s_cmp_eq_u32 s74, 60
	s_cselect_b32 s35, s23, s35
	s_cselect_b32 s34, s27, s34
	s_cselect_b32 s43, s21, s73
	s_cselect_b32 s42, s39, s72
	s_add_i32 m0, s45, 0xc000
	ds_read_b128 v[186:189], v156
	ds_read_b128 v[190:193], v156 offset:1024
	ds_read_b128 v[194:197], v156 offset:2048
	ds_read_b128 v[198:201], v156 offset:3072
	ds_read_b128 v[202:205], v156 offset:4096
	ds_read_b128 v[206:209], v156 offset:5120
	ds_read_b128 v[210:213], v156 offset:6144
	ds_read_b128 v[214:217], v156 offset:7168
	global_load_lds_dwordx4 v138, s[40:41]
	s_add_i32 m0, s45, 0xe000
	s_nop 0
	global_load_lds_dwordx4 v140, s[40:41]
	s_waitcnt vmcnt(8)
	s_waitcnt lgkmcnt(0)
	s_barrier
	s_setprio 1
	s_waitcnt lgkmcnt(0)
	v_mfma_f32_16x16x32_bf16 v[126:129], v[146:149], v[186:189], v[126:129]
	v_mfma_f32_16x16x32_bf16 v[122:125], v[162:165], v[186:189], v[122:125]
	v_mfma_f32_16x16x32_bf16 v[118:121], v[146:149], v[194:197], v[118:121]
	v_mfma_f32_16x16x32_bf16 v[114:117], v[162:165], v[194:197], v[114:117]
	v_mfma_f32_16x16x32_bf16 v[110:113], v[146:149], v[202:205], v[110:113]
	v_mfma_f32_16x16x32_bf16 v[106:109], v[162:165], v[202:205], v[106:109]
	v_mfma_f32_16x16x32_bf16 v[102:105], v[146:149], v[210:213], v[102:105]
	v_mfma_f32_16x16x32_bf16 v[98:101], v[162:165], v[210:213], v[98:101]
	v_mfma_f32_16x16x32_bf16 v[126:129], v[158:161], v[190:193], v[126:129]
	v_mfma_f32_16x16x32_bf16 v[122:125], v[166:169], v[190:193], v[122:125]
	v_mfma_f32_16x16x32_bf16 v[118:121], v[158:161], v[198:201], v[118:121]
	v_mfma_f32_16x16x32_bf16 v[114:117], v[166:169], v[198:201], v[114:117]
	v_mfma_f32_16x16x32_bf16 v[110:113], v[158:161], v[206:209], v[110:113]
	v_mfma_f32_16x16x32_bf16 v[106:109], v[166:169], v[206:209], v[106:109]
	v_mfma_f32_16x16x32_bf16 v[102:105], v[158:161], v[214:217], v[102:105]
	v_mfma_f32_16x16x32_bf16 v[98:101], v[166:169], v[214:217], v[98:101]
	s_setprio 0
	s_setprio 1
	v_mfma_f32_16x16x32_bf16 v[62:65], v[170:173], v[186:189], v[62:65]
	v_mfma_f32_16x16x32_bf16 v[58:61], v[178:181], v[186:189], v[58:61]
	v_mfma_f32_16x16x32_bf16 v[54:57], v[170:173], v[194:197], v[54:57]
	v_mfma_f32_16x16x32_bf16 v[50:53], v[178:181], v[194:197], v[50:53]
	v_mfma_f32_16x16x32_bf16 v[46:49], v[170:173], v[202:205], v[46:49]
	v_mfma_f32_16x16x32_bf16 v[42:45], v[178:181], v[202:205], v[42:45]
	v_mfma_f32_16x16x32_bf16 v[38:41], v[170:173], v[210:213], v[38:41]
	v_mfma_f32_16x16x32_bf16 v[34:37], v[178:181], v[210:213], v[34:37]
	v_mfma_f32_16x16x32_bf16 v[62:65], v[174:177], v[190:193], v[62:65]
	v_mfma_f32_16x16x32_bf16 v[58:61], v[182:185], v[190:193], v[58:61]
	v_mfma_f32_16x16x32_bf16 v[54:57], v[174:177], v[198:201], v[54:57]
	v_mfma_f32_16x16x32_bf16 v[50:53], v[182:185], v[198:201], v[50:53]
	v_mfma_f32_16x16x32_bf16 v[46:49], v[174:177], v[206:209], v[46:49]
	v_mfma_f32_16x16x32_bf16 v[42:45], v[182:185], v[206:209], v[42:45]
	v_mfma_f32_16x16x32_bf16 v[38:41], v[174:177], v[214:217], v[38:41]
	v_mfma_f32_16x16x32_bf16 v[34:37], v[182:185], v[214:217], v[34:37]
	s_setprio 0
	s_barrier
	s_add_i32 s75, s64, s17
	s_add_u32 s98, s42, 0x80
	s_addc_u32 s99, s43, 0
	s_add_u32 s100, s34, 0x80
	s_addc_u32 s101, s35, 0
	s_mov_b32 m0, s75
	ds_read_b128 v[186:189], v156 offset:16384
	ds_read_b128 v[190:193], v156 offset:17408
	ds_read_b128 v[194:197], v156 offset:18432
	ds_read_b128 v[198:201], v156 offset:19456
	ds_read_b128 v[202:205], v156 offset:20480
	ds_read_b128 v[206:209], v156 offset:21504
	ds_read_b128 v[210:213], v156 offset:22528
	ds_read_b128 v[214:217], v156 offset:23552
	global_load_lds_dwordx4 v134, s[42:43]
	s_add_i32 m0, s75, 0x2000
	s_add_u32 s76, s42, 0x100000
	s_addc_u32 s77, s43, 0
	s_add_i32 s75, s65, s17
	global_load_lds_dwordx4 v130, s[42:43]
	s_mov_b32 m0, s75
	s_nop 0
	global_load_lds_dwordx4 v134, s[76:77]
	s_add_i32 m0, s75, 0x2000
	s_nop 0
	global_load_lds_dwordx4 v130, s[76:77]
	s_mov_b32 m0, s45
	s_nop 0
	global_load_lds_dwordx4 v136, s[34:35]
	s_mov_b32 m0, s46
	s_nop 0
	global_load_lds_dwordx4 v132, s[34:35]
	s_waitcnt vmcnt(8)
	s_waitcnt lgkmcnt(0)
	s_barrier
	s_setprio 1
	s_waitcnt lgkmcnt(0)
	v_mfma_f32_16x16x32_bf16 v[94:97], v[146:149], v[186:189], v[94:97]
	v_mfma_f32_16x16x32_bf16 v[90:93], v[162:165], v[186:189], v[90:93]
	v_mfma_f32_16x16x32_bf16 v[86:89], v[146:149], v[194:197], v[86:89]
	v_mfma_f32_16x16x32_bf16 v[82:85], v[162:165], v[194:197], v[82:85]
	v_mfma_f32_16x16x32_bf16 v[78:81], v[146:149], v[202:205], v[78:81]
	v_mfma_f32_16x16x32_bf16 v[74:77], v[162:165], v[202:205], v[74:77]
	v_mfma_f32_16x16x32_bf16 v[70:73], v[146:149], v[210:213], v[70:73]
	v_mfma_f32_16x16x32_bf16 v[66:69], v[162:165], v[210:213], v[66:69]
	v_mfma_f32_16x16x32_bf16 v[94:97], v[158:161], v[190:193], v[94:97]
	v_mfma_f32_16x16x32_bf16 v[90:93], v[166:169], v[190:193], v[90:93]
	v_mfma_f32_16x16x32_bf16 v[86:89], v[158:161], v[198:201], v[86:89]
	v_mfma_f32_16x16x32_bf16 v[82:85], v[166:169], v[198:201], v[82:85]
	v_mfma_f32_16x16x32_bf16 v[78:81], v[158:161], v[206:209], v[78:81]
	v_mfma_f32_16x16x32_bf16 v[74:77], v[166:169], v[206:209], v[74:77]
	v_mfma_f32_16x16x32_bf16 v[70:73], v[158:161], v[214:217], v[70:73]
	v_mfma_f32_16x16x32_bf16 v[66:69], v[166:169], v[214:217], v[66:69]
	s_setprio 0
	s_setprio 1
	v_mfma_f32_16x16x32_bf16 v[30:33], v[170:173], v[186:189], v[30:33]
	v_mfma_f32_16x16x32_bf16 v[26:29], v[178:181], v[186:189], v[26:29]
	v_mfma_f32_16x16x32_bf16 v[22:25], v[170:173], v[194:197], v[22:25]
	v_mfma_f32_16x16x32_bf16 v[18:21], v[178:181], v[194:197], v[18:21]
	v_mfma_f32_16x16x32_bf16 v[14:17], v[170:173], v[202:205], v[14:17]
	v_mfma_f32_16x16x32_bf16 v[10:13], v[178:181], v[202:205], v[10:13]
	v_mfma_f32_16x16x32_bf16 v[6:9], v[170:173], v[210:213], v[6:9]
	v_mfma_f32_16x16x32_bf16 v[2:5], v[178:181], v[210:213], v[2:5]
	v_mfma_f32_16x16x32_bf16 v[30:33], v[174:177], v[190:193], v[30:33]
	v_mfma_f32_16x16x32_bf16 v[26:29], v[182:185], v[190:193], v[26:29]
	v_mfma_f32_16x16x32_bf16 v[22:25], v[174:177], v[198:201], v[22:25]
	v_mfma_f32_16x16x32_bf16 v[18:21], v[182:185], v[198:201], v[18:21]
	v_mfma_f32_16x16x32_bf16 v[14:17], v[174:177], v[206:209], v[14:17]
	v_mfma_f32_16x16x32_bf16 v[10:13], v[182:185], v[206:209], v[10:13]
	v_mfma_f32_16x16x32_bf16 v[6:9], v[174:177], v[214:217], v[6:9]
	v_mfma_f32_16x16x32_bf16 v[2:5], v[182:185], v[214:217], v[2:5]
	s_setprio 0
	s_barrier
; #define PG8_STAGE(bufoff, gbase, voff) do { _Pragma("unroll") for (int _i = 0; _i < 2; ++_i) \
;         __builtin_amdgcn_global_load_lds((const unsigned*)((const char*)(gbase) + (voff)[_i]), (PG8_LAS unsigned*)(lds + (bufoff) + ldsw + _i * 8192), 16, 0, 0); } while (0)
; #define PG8_LDA(dst, b, h) do { _Pragma("unroll") for (int m = 0; m < 4; ++m) _Pragma("unroll") for (int k = 0; k < 2; ++k) dst[m][k] = *(const PG8_LAS bf16x8*)(lds + PG8_SA(b, h) + aoff + m * 2048 + k * 1024); } while (0)
; #define PG8_LDB(dst, b, h) do { _Pragma("unroll") for (int n = 0; n < 2; ++n) _Pragma("unroll") for (int k = 0; k < 2; ++k) dst[n][k] = *(const PG8_LAS bf16x8*)(lds + PG8_SB(b, h) + boff + n * 2048 + k * 1024); } while (0)
; #define PG8_MMA(ai, bj, At, Bt) do { __builtin_amdgcn_s_setprio(1); _Pragma("unroll") for (int m = 0; m < 4; ++m) _Pragma("unroll") for (int n = 0; n < 2; ++n) _Pragma("unroll") for (int k = 0; k < 2; ++k) \
;         acc[ai][bj][m][n] = __builtin_amdgcn_mfma_f32_16x16x32_bf16(Bt[n][k], At[m][k], acc[ai][bj][m][n], 0, 0, 0); __builtin_amdgcn_s_setprio(0); } while (0)
; #define PG8_WAIT_V(n) asm volatile("s_waitcnt vmcnt(" #n ")" ::: "memory")
; #define PG8_WAIT_L(n) asm volatile("s_waitcnt lgkmcnt(" #n ")" ::: "memory")
; #define PG8_BAR __builtin_amdgcn_s_barrier()
; #define PG8_SCHED __builtin_amdgcn_sched_barrier(0)
; template <class Epi, class Sched, bool ALIGN_EPI = false, bool SP2 = false>
; __device__ __forceinline__ void gemm_phase(PG8_LAS unsigned char* lds, const Gemm g, const Sched& S, const Epi& E) {
;     ...
;             PG8_LDB(B0, 1, 0); PG8_LDB(B1, 1, 1); PG8_SCHED; PG8_LDA(At, 1, 0); PG8_STAGE(PG8_SA(0, 1), a2 + hstepA, voffA);
;             PG8_WAIT_V(8); PG8_WAIT_L(0); PG8_BAR; PG8_MMA(0, 0, At, B0); PG8_MMA(0, 1, At, B1); PG8_BAR; PG8_SCHED;
;             PG8_LDA(At, 1, 1); PG8_STAGE(PG8_SB(1, 0), b3, voffB); PG8_STAGE(PG8_SB(1, 1), b3 + hstepB, voffB); PG8_STAGE(PG8_SA(1, 0), a3, voffA);
;             PG8_WAIT_V(8); PG8_WAIT_L(0); PG8_BAR; PG8_MMA(1, 0, At, B0); PG8_MMA(1, 1, At, B1); PG8_BAR; PG8_SCHED;
	s_add_i32 s75, 0, 0x18000
	v_add_u32_e32 v157, s75, v152
	s_add_i32 s76, 0, 0x1c000
	ds_read_b128 v[146:149], v157
	ds_read_b128 v[158:161], v157 offset:1024
	ds_read_b128 v[162:165], v157 offset:2048
	ds_read_b128 v[166:169], v157 offset:3072
	v_add_u32_e32 v157, s76, v152
	ds_read_b128 v[170:173], v157
	ds_read_b128 v[174:177], v157 offset:1024
	ds_read_b128 v[178:181], v157 offset:2048
	ds_read_b128 v[182:185], v157 offset:3072
	s_add_u32 s34, s34, 0x100000
	s_addc_u32 s35, s35, 0
	s_mov_b32 m0, s47
	ds_read_b128 v[186:189], v156 offset:32768
	ds_read_b128 v[190:193], v156 offset:33792
	ds_read_b128 v[194:197], v156 offset:34816
	ds_read_b128 v[198:201], v156 offset:35840
	ds_read_b128 v[202:205], v156 offset:36864
	ds_read_b128 v[206:209], v156 offset:37888
	ds_read_b128 v[210:213], v156 offset:38912
	ds_read_b128 v[214:217], v156 offset:39936
	global_load_lds_dwordx4 v136, s[34:35]
	s_mov_b32 m0, s48
	s_nop 0
	global_load_lds_dwordx4 v132, s[34:35]
	s_waitcnt vmcnt(8)
	s_waitcnt lgkmcnt(0)
	s_barrier
	s_setprio 1
	s_waitcnt lgkmcnt(0)
	v_mfma_f32_16x16x32_bf16 v[126:129], v[146:149], v[186:189], v[126:129]
	v_mfma_f32_16x16x32_bf16 v[122:125], v[162:165], v[186:189], v[122:125]
	v_mfma_f32_16x16x32_bf16 v[118:121], v[146:149], v[194:197], v[118:121]
	v_mfma_f32_16x16x32_bf16 v[114:117], v[162:165], v[194:197], v[114:117]
	v_mfma_f32_16x16x32_bf16 v[110:113], v[146:149], v[202:205], v[110:113]
	v_mfma_f32_16x16x32_bf16 v[106:109], v[162:165], v[202:205], v[106:109]
	v_mfma_f32_16x16x32_bf16 v[102:105], v[146:149], v[210:213], v[102:105]
	v_mfma_f32_16x16x32_bf16 v[98:101], v[162:165], v[210:213], v[98:101]
	v_mfma_f32_16x16x32_bf16 v[126:129], v[158:161], v[190:193], v[126:129]
	v_mfma_f32_16x16x32_bf16 v[122:125], v[166:169], v[190:193], v[122:125]
	v_mfma_f32_16x16x32_bf16 v[118:121], v[158:161], v[198:201], v[118:121]
	v_mfma_f32_16x16x32_bf16 v[114:117], v[166:169], v[198:201], v[114:117]
	v_mfma_f32_16x16x32_bf16 v[110:113], v[158:161], v[206:209], v[110:113]
	v_mfma_f32_16x16x32_bf16 v[106:109], v[166:169], v[206:209], v[106:109]
	v_mfma_f32_16x16x32_bf16 v[102:105], v[158:161], v[214:217], v[102:105]
	v_mfma_f32_16x16x32_bf16 v[98:101], v[166:169], v[214:217], v[98:101]
	s_setprio 0
	s_setprio 1
	v_mfma_f32_16x16x32_bf16 v[62:65], v[170:173], v[186:189], v[62:65]
	v_mfma_f32_16x16x32_bf16 v[58:61], v[178:181], v[186:189], v[58:61]
	v_mfma_f32_16x16x32_bf16 v[54:57], v[170:173], v[194:197], v[54:57]
	v_mfma_f32_16x16x32_bf16 v[50:53], v[178:181], v[194:197], v[50:53]
	v_mfma_f32_16x16x32_bf16 v[46:49], v[170:173], v[202:205], v[46:49]
	v_mfma_f32_16x16x32_bf16 v[42:45], v[178:181], v[202:205], v[42:45]
	v_mfma_f32_16x16x32_bf16 v[38:41], v[170:173], v[210:213], v[38:41]
	v_mfma_f32_16x16x32_bf16 v[34:37], v[178:181], v[210:213], v[34:37]
	v_mfma_f32_16x16x32_bf16 v[62:65], v[174:177], v[190:193], v[62:65]
	v_mfma_f32_16x16x32_bf16 v[58:61], v[182:185], v[190:193], v[58:61]
	v_mfma_f32_16x16x32_bf16 v[54:57], v[174:177], v[198:201], v[54:57]
	v_mfma_f32_16x16x32_bf16 v[50:53], v[182:185], v[198:201], v[50:53]
	v_mfma_f32_16x16x32_bf16 v[46:49], v[174:177], v[206:209], v[46:49]
	v_mfma_f32_16x16x32_bf16 v[42:45], v[182:185], v[206:209], v[42:45]
	v_mfma_f32_16x16x32_bf16 v[38:41], v[174:177], v[214:217], v[38:41]
	v_mfma_f32_16x16x32_bf16 v[34:37], v[182:185], v[214:217], v[34:37]
	s_setprio 0
	s_barrier
	s_add_i32 s34, s75, s17
	s_mov_b32 m0, s34
	ds_read_b128 v[186:189], v156 offset:49152
	ds_read_b128 v[190:193], v156 offset:50176
	ds_read_b128 v[194:197], v156 offset:51200
	ds_read_b128 v[198:201], v156 offset:52224
	ds_read_b128 v[202:205], v156 offset:53248
	ds_read_b128 v[206:209], v156 offset:54272
	ds_read_b128 v[210:213], v156 offset:55296
	ds_read_b128 v[214:217], v156 offset:56320
	global_load_lds_dwordx4 v134, s[98:99]
	s_add_i32 m0, s34, 0x2000
	s_add_u32 s34, s42, 0x100080
	s_addc_u32 s35, s43, 0
	s_add_i32 s42, s76, s17
	global_load_lds_dwordx4 v130, s[98:99]
	s_mov_b32 m0, s42
	s_nop 0
	global_load_lds_dwordx4 v134, s[34:35]
	s_add_i32 m0, s42, 0x2000
	s_nop 0
	global_load_lds_dwordx4 v130, s[34:35]
	s_mov_b32 m0, s52
	s_nop 0
	global_load_lds_dwordx4 v136, s[100:101]
	s_mov_b32 m0, s53
	s_nop 0
	global_load_lds_dwordx4 v132, s[100:101]
	s_waitcnt vmcnt(8)
	s_waitcnt lgkmcnt(0)
	s_barrier
	s_setprio 1
	s_waitcnt lgkmcnt(0)
	v_mfma_f32_16x16x32_bf16 v[94:97], v[146:149], v[186:189], v[94:97]
	v_mfma_f32_16x16x32_bf16 v[90:93], v[162:165], v[186:189], v[90:93]
	v_mfma_f32_16x16x32_bf16 v[86:89], v[146:149], v[194:197], v[86:89]
	v_mfma_f32_16x16x32_bf16 v[82:85], v[162:165], v[194:197], v[82:85]
	v_mfma_f32_16x16x32_bf16 v[78:81], v[146:149], v[202:205], v[78:81]
	v_mfma_f32_16x16x32_bf16 v[74:77], v[162:165], v[202:205], v[74:77]
	v_mfma_f32_16x16x32_bf16 v[70:73], v[146:149], v[210:213], v[70:73]
	v_mfma_f32_16x16x32_bf16 v[66:69], v[162:165], v[210:213], v[66:69]
	v_mfma_f32_16x16x32_bf16 v[94:97], v[158:161], v[190:193], v[94:97]
	v_mfma_f32_16x16x32_bf16 v[90:93], v[166:169], v[190:193], v[90:93]
	v_mfma_f32_16x16x32_bf16 v[86:89], v[158:161], v[198:201], v[86:89]
	v_mfma_f32_16x16x32_bf16 v[82:85], v[166:169], v[198:201], v[82:85]
	v_mfma_f32_16x16x32_bf16 v[78:81], v[158:161], v[206:209], v[78:81]
	v_mfma_f32_16x16x32_bf16 v[74:77], v[166:169], v[206:209], v[74:77]
	v_mfma_f32_16x16x32_bf16 v[70:73], v[158:161], v[214:217], v[70:73]
	v_mfma_f32_16x16x32_bf16 v[66:69], v[166:169], v[214:217], v[66:69]
	s_setprio 0
	s_setprio 1
	v_mfma_f32_16x16x32_bf16 v[30:33], v[170:173], v[186:189], v[30:33]
	v_mfma_f32_16x16x32_bf16 v[26:29], v[178:181], v[186:189], v[26:29]
	v_mfma_f32_16x16x32_bf16 v[22:25], v[170:173], v[194:197], v[22:25]
	v_mfma_f32_16x16x32_bf16 v[18:21], v[178:181], v[194:197], v[18:21]
	v_mfma_f32_16x16x32_bf16 v[14:17], v[170:173], v[202:205], v[14:17]
	v_mfma_f32_16x16x32_bf16 v[10:13], v[178:181], v[202:205], v[10:13]
	v_mfma_f32_16x16x32_bf16 v[6:9], v[170:173], v[210:213], v[6:9]
	v_mfma_f32_16x16x32_bf16 v[2:5], v[178:181], v[210:213], v[2:5]
	v_mfma_f32_16x16x32_bf16 v[30:33], v[174:177], v[190:193], v[30:33]
	v_mfma_f32_16x16x32_bf16 v[26:29], v[182:185], v[190:193], v[26:29]
	v_mfma_f32_16x16x32_bf16 v[22:25], v[174:177], v[198:201], v[22:25]
	v_mfma_f32_16x16x32_bf16 v[18:21], v[182:185], v[198:201], v[18:21]
	v_mfma_f32_16x16x32_bf16 v[14:17], v[174:177], v[206:209], v[14:17]
	v_mfma_f32_16x16x32_bf16 v[10:13], v[182:185], v[206:209], v[10:13]
	v_mfma_f32_16x16x32_bf16 v[6:9], v[174:177], v[214:217], v[6:9]
	v_mfma_f32_16x16x32_bf16 v[2:5], v[182:185], v[214:217], v[2:5]
	s_setprio 0
	s_barrier
	s_add_i32 s74, s74, 2
	s_add_u32 s40, s40, 0x100
	s_addc_u32 s41, s41, 0
	s_add_u32 s72, s72, 0x100
	s_addc_u32 s73, s73, 0
	s_cmp_gt_u32 s74, 61
	s_cbranch_scc0 .LBB0_990
	s_and_b64 vcc, exec, s[12:13]
	s_cbranch_vccz .LBB0_993
	s_barrier

; #define PG8_STAGE(bufoff, gbase, voff) do { _Pragma("unroll") for (int _i = 0; _i < 2; ++_i) \
;         __builtin_amdgcn_global_load_lds((const unsigned*)((const char*)(gbase) + (voff)[_i]), (PG8_LAS unsigned*)(lds + (bufoff) + ldsw + _i * 8192), 16, 0, 0); } while (0)
; #define PG8_LDA(dst, b, h) do { _Pragma("unroll") for (int m = 0; m < 4; ++m) _Pragma("unroll") for (int k = 0; k < 2; ++k) dst[m][k] = *(const PG8_LAS bf16x8*)(lds + PG8_SA(b, h) + aoff + m * 2048 + k * 1024); } while (0)
; #define PG8_LDB(dst, b, h) do { _Pragma("unroll") for (int n = 0; n < 2; ++n) _Pragma("unroll") for (int k = 0; k < 2; ++k) dst[n][k] = *(const PG8_LAS bf16x8*)(lds + PG8_SB(b, h) + boff + n * 2048 + k * 1024); } while (0)
; #define PG8_MMA(ai, bj, At, Bt) do { __builtin_amdgcn_s_setprio(1); _Pragma("unroll") for (int m = 0; m < 4; ++m) _Pragma("unroll") for (int n = 0; n < 2; ++n) _Pragma("unroll") for (int k = 0; k < 2; ++k) \
;         acc[ai][bj][m][n] = __builtin_amdgcn_mfma_f32_16x16x32_bf16(Bt[n][k], At[m][k], acc[ai][bj][m][n], 0, 0, 0); __builtin_amdgcn_s_setprio(0); } while (0)
; #define PG8_WAIT_V(n) asm volatile("s_waitcnt vmcnt(" #n ")" ::: "memory")
; #define PG8_WAIT_L(n) asm volatile("s_waitcnt lgkmcnt(" #n ")" ::: "memory")
; #define PG8_BAR __builtin_amdgcn_s_barrier()
; #define PG8_SCHED __builtin_amdgcn_sched_barrier(0)
; template <class Epi, class Sched, bool ALIGN_EPI = false, bool SP2 = false>
; __device__ __forceinline__ void gemm_phase(PG8_LAS unsigned char* lds, const Gemm g, const Sched& S, const Epi& E) {
;     ...
;             PG8_LDB(B0, 0, 0); PG8_LDB(B1, 0, 1); PG8_SCHED; PG8_LDA(At, 0, 0); PG8_STAGE(PG8_SA(1, 1), a1 + hstepA, voffA);
;             PG8_WAIT_V(8); PG8_WAIT_L(0); PG8_BAR; PG8_MMA(0, 0, At, B0); PG8_MMA(0, 1, At, B1); PG8_BAR; PG8_SCHED;
;             PG8_LDA(At, 0, 1); PG8_STAGE(PG8_SB(0, 0), b2, voffB); PG8_STAGE(PG8_SB(0, 1), b2 + hstepB, voffB); PG8_STAGE(PG8_SA(0, 0), a2, voffA);
;             PG8_WAIT_V(8); PG8_WAIT_L(0); PG8_BAR; PG8_MMA(1, 0, At, B0); PG8_MMA(1, 1, At, B1); PG8_BAR; PG8_SCHED;
.LBB0_1127:
	ds_read_b128 v[130:133], v203
	ds_read_b128 v[134:137], v203 offset:1024
	ds_read_b128 v[138:141], v203 offset:2048
	ds_read_b128 v[142:145], v203 offset:3072
	ds_read_b128 v[146:149], v205
	ds_read_b128 v[150:153], v205 offset:1024
	ds_read_b128 v[154:157], v205 offset:2048
	ds_read_b128 v[158:161], v205 offset:3072
	s_add_u32 s34, s40, 0xfff00080
	s_addc_u32 s35, s41, -1
	s_cmp_eq_u32 s53, 60
	s_cselect_b32 s35, s25, s35
	s_cselect_b32 s34, s26, s34
	s_cselect_b32 s43, s23, s52
	s_cselect_b32 s42, s27, s45
	s_add_i32 m0, s47, 0xc000
	ds_read_b128 v[162:165], v207
	ds_read_b128 v[166:169], v207 offset:1024
	ds_read_b128 v[170:173], v207 offset:2048
	ds_read_b128 v[174:177], v207 offset:3072
	ds_read_b128 v[196:199], v207 offset:4096
	ds_read_b128 v[208:211], v207 offset:5120
	ds_read_b128 v[212:215], v207 offset:6144
	ds_read_b128 v[216:219], v207 offset:7168
	global_load_lds_dwordx4 v188, s[40:41]
	s_add_i32 m0, s47, 0xe000
	s_nop 0
	global_load_lds_dwordx4 v190, s[40:41]
	s_waitcnt vmcnt(8)
	s_waitcnt lgkmcnt(0)
	s_barrier
	s_setprio 1
	s_waitcnt lgkmcnt(0)
	v_mfma_f32_16x16x32_bf16 v[122:125], v[130:133], v[162:165], v[122:125]
	v_mfma_f32_16x16x32_bf16 v[118:121], v[138:141], v[162:165], v[118:121]
	v_mfma_f32_16x16x32_bf16 v[106:109], v[130:133], v[170:173], v[106:109]
	v_mfma_f32_16x16x32_bf16 v[102:105], v[138:141], v[170:173], v[102:105]
	v_mfma_f32_16x16x32_bf16 v[90:93], v[130:133], v[196:199], v[90:93]
	v_mfma_f32_16x16x32_bf16 v[86:89], v[138:141], v[196:199], v[86:89]
	v_mfma_f32_16x16x32_bf16 v[74:77], v[130:133], v[212:215], v[74:77]
	v_mfma_f32_16x16x32_bf16 v[70:73], v[138:141], v[212:215], v[70:73]
	v_mfma_f32_16x16x32_bf16 v[122:125], v[134:137], v[166:169], v[122:125]
	v_mfma_f32_16x16x32_bf16 v[118:121], v[142:145], v[166:169], v[118:121]
	v_mfma_f32_16x16x32_bf16 v[106:109], v[134:137], v[174:177], v[106:109]
	v_mfma_f32_16x16x32_bf16 v[102:105], v[142:145], v[174:177], v[102:105]
	v_mfma_f32_16x16x32_bf16 v[90:93], v[134:137], v[208:211], v[90:93]
	v_mfma_f32_16x16x32_bf16 v[86:89], v[142:145], v[208:211], v[86:89]
	v_mfma_f32_16x16x32_bf16 v[74:77], v[134:137], v[216:219], v[74:77]
	v_mfma_f32_16x16x32_bf16 v[70:73], v[142:145], v[216:219], v[70:73]
	s_setprio 0
	s_setprio 1
	v_mfma_f32_16x16x32_bf16 v[126:129], v[146:149], v[162:165], v[126:129]
	v_mfma_f32_16x16x32_bf16 v[114:117], v[154:157], v[162:165], v[114:117]
	v_mfma_f32_16x16x32_bf16 v[110:113], v[146:149], v[170:173], v[110:113]
	v_mfma_f32_16x16x32_bf16 v[98:101], v[154:157], v[170:173], v[98:101]
	v_mfma_f32_16x16x32_bf16 v[94:97], v[146:149], v[196:199], v[94:97]
	v_mfma_f32_16x16x32_bf16 v[82:85], v[154:157], v[196:199], v[82:85]
	v_mfma_f32_16x16x32_bf16 v[78:81], v[146:149], v[212:215], v[78:81]
	v_mfma_f32_16x16x32_bf16 v[66:69], v[154:157], v[212:215], v[66:69]
	v_mfma_f32_16x16x32_bf16 v[126:129], v[150:153], v[166:169], v[126:129]
	v_mfma_f32_16x16x32_bf16 v[114:117], v[158:161], v[166:169], v[114:117]
	v_mfma_f32_16x16x32_bf16 v[110:113], v[150:153], v[174:177], v[110:113]
	v_mfma_f32_16x16x32_bf16 v[98:101], v[158:161], v[174:177], v[98:101]
	v_mfma_f32_16x16x32_bf16 v[94:97], v[150:153], v[208:211], v[94:97]
	v_mfma_f32_16x16x32_bf16 v[82:85], v[158:161], v[208:211], v[82:85]
	v_mfma_f32_16x16x32_bf16 v[78:81], v[150:153], v[216:219], v[78:81]
	v_mfma_f32_16x16x32_bf16 v[66:69], v[158:161], v[216:219], v[66:69]
	s_setprio 0
	s_barrier
	s_add_i32 s73, s68, s17
	s_add_u32 s98, s42, 0x80
	s_addc_u32 s99, s43, 0
	s_add_u32 s100, s34, 0x80
	s_addc_u32 s101, s35, 0
	s_mov_b32 m0, s73
	ds_read_b128 v[162:165], v207 offset:16384
	ds_read_b128 v[166:169], v207 offset:17408
	ds_read_b128 v[170:173], v207 offset:18432
	ds_read_b128 v[174:177], v207 offset:19456
	ds_read_b128 v[196:199], v207 offset:20480
	ds_read_b128 v[208:211], v207 offset:21504
	ds_read_b128 v[212:215], v207 offset:22528
	ds_read_b128 v[216:219], v207 offset:23552
	global_load_lds_dwordx4 v182, s[42:43]
	s_add_i32 m0, s73, 0x2000
	s_add_u32 s74, s42, 0x100000
	s_addc_u32 s75, s43, 0
	s_add_i32 s73, s69, s17
	global_load_lds_dwordx4 v178, s[42:43]
	s_mov_b32 m0, s73
	s_nop 0
	global_load_lds_dwordx4 v182, s[74:75]
	s_add_i32 m0, s73, 0x2000
	s_nop 0
	global_load_lds_dwordx4 v178, s[74:75]
	s_mov_b32 m0, s47
	s_nop 0
	global_load_lds_dwordx4 v184, s[34:35]
	s_mov_b32 m0, s48
	s_nop 0
	global_load_lds_dwordx4 v180, s[34:35]
	s_waitcnt vmcnt(8)
	s_waitcnt lgkmcnt(0)
	s_barrier
	s_setprio 1
	s_waitcnt lgkmcnt(0)
	v_mfma_f32_16x16x32_bf16 v[58:61], v[130:133], v[162:165], v[58:61]
	v_mfma_f32_16x16x32_bf16 v[54:57], v[138:141], v[162:165], v[54:57]
	v_mfma_f32_16x16x32_bf16 v[42:45], v[130:133], v[170:173], v[42:45]
	v_mfma_f32_16x16x32_bf16 v[38:41], v[138:141], v[170:173], v[38:41]
	v_mfma_f32_16x16x32_bf16 v[26:29], v[130:133], v[196:199], v[26:29]
	v_mfma_f32_16x16x32_bf16 v[22:25], v[138:141], v[196:199], v[22:25]
	v_mfma_f32_16x16x32_bf16 v[10:13], v[130:133], v[212:215], v[10:13]
	v_mfma_f32_16x16x32_bf16 v[6:9], v[138:141], v[212:215], v[6:9]
	v_mfma_f32_16x16x32_bf16 v[58:61], v[134:137], v[166:169], v[58:61]
	v_mfma_f32_16x16x32_bf16 v[54:57], v[142:145], v[166:169], v[54:57]
	v_mfma_f32_16x16x32_bf16 v[42:45], v[134:137], v[174:177], v[42:45]
	v_mfma_f32_16x16x32_bf16 v[38:41], v[142:145], v[174:177], v[38:41]
	v_mfma_f32_16x16x32_bf16 v[26:29], v[134:137], v[208:211], v[26:29]
	v_mfma_f32_16x16x32_bf16 v[22:25], v[142:145], v[208:211], v[22:25]
	v_mfma_f32_16x16x32_bf16 v[10:13], v[134:137], v[216:219], v[10:13]
	v_mfma_f32_16x16x32_bf16 v[6:9], v[142:145], v[216:219], v[6:9]
	s_setprio 0
	s_setprio 1
	v_mfma_f32_16x16x32_bf16 v[62:65], v[146:149], v[162:165], v[62:65]
	v_mfma_f32_16x16x32_bf16 v[50:53], v[154:157], v[162:165], v[50:53]
	v_mfma_f32_16x16x32_bf16 v[46:49], v[146:149], v[170:173], v[46:49]
	v_mfma_f32_16x16x32_bf16 v[34:37], v[154:157], v[170:173], v[34:37]
	v_mfma_f32_16x16x32_bf16 v[30:33], v[146:149], v[196:199], v[30:33]
	v_mfma_f32_16x16x32_bf16 v[18:21], v[154:157], v[196:199], v[18:21]
	v_mfma_f32_16x16x32_bf16 v[14:17], v[146:149], v[212:215], v[14:17]
	v_mfma_f32_16x16x32_bf16 v[2:5], v[154:157], v[212:215], v[2:5]
	v_mfma_f32_16x16x32_bf16 v[62:65], v[150:153], v[166:169], v[62:65]
	v_mfma_f32_16x16x32_bf16 v[50:53], v[158:161], v[166:169], v[50:53]
	v_mfma_f32_16x16x32_bf16 v[46:49], v[150:153], v[174:177], v[46:49]
	v_mfma_f32_16x16x32_bf16 v[34:37], v[158:161], v[174:177], v[34:37]
	v_mfma_f32_16x16x32_bf16 v[30:33], v[150:153], v[208:211], v[30:33]
	v_mfma_f32_16x16x32_bf16 v[18:21], v[158:161], v[208:211], v[18:21]
	v_mfma_f32_16x16x32_bf16 v[14:17], v[150:153], v[216:219], v[14:17]
	v_mfma_f32_16x16x32_bf16 v[2:5], v[158:161], v[216:219], v[2:5]
	s_setprio 0
	s_barrier
; #define PG8_STAGE(bufoff, gbase, voff) do { _Pragma("unroll") for (int _i = 0; _i < 2; ++_i) \
;         __builtin_amdgcn_global_load_lds((const unsigned*)((const char*)(gbase) + (voff)[_i]), (PG8_LAS unsigned*)(lds + (bufoff) + ldsw + _i * 8192), 16, 0, 0); } while (0)
; #define PG8_LDA(dst, b, h) do { _Pragma("unroll") for (int m = 0; m < 4; ++m) _Pragma("unroll") for (int k = 0; k < 2; ++k) dst[m][k] = *(const PG8_LAS bf16x8*)(lds + PG8_SA(b, h) + aoff + m * 2048 + k * 1024); } while (0)
; #define PG8_LDB(dst, b, h) do { _Pragma("unroll") for (int n = 0; n < 2; ++n) _Pragma("unroll") for (int k = 0; k < 2; ++k) dst[n][k] = *(const PG8_LAS bf16x8*)(lds + PG8_SB(b, h) + boff + n * 2048 + k * 1024); } while (0)
; #define PG8_MMA(ai, bj, At, Bt) do { __builtin_amdgcn_s_setprio(1); _Pragma("unroll") for (int m = 0; m < 4; ++m) _Pragma("unroll") for (int n = 0; n < 2; ++n) _Pragma("unroll") for (int k = 0; k < 2; ++k) \
;         acc[ai][bj][m][n] = __builtin_amdgcn_mfma_f32_16x16x32_bf16(Bt[n][k], At[m][k], acc[ai][bj][m][n], 0, 0, 0); __builtin_amdgcn_s_setprio(0); } while (0)
; #define PG8_WAIT_V(n) asm volatile("s_waitcnt vmcnt(" #n ")" ::: "memory")
; #define PG8_WAIT_L(n) asm volatile("s_waitcnt lgkmcnt(" #n ")" ::: "memory")
; #define PG8_BAR __builtin_amdgcn_s_barrier()
; #define PG8_SCHED __builtin_amdgcn_sched_barrier(0)
; template <class Epi, class Sched, bool ALIGN_EPI = false, bool SP2 = false>
; __device__ __forceinline__ void gemm_phase(PG8_LAS unsigned char* lds, const Gemm g, const Sched& S, const Epi& E) {
;     ...
;             PG8_LDB(B0, 1, 0); PG8_LDB(B1, 1, 1); PG8_SCHED; PG8_LDA(At, 1, 0); PG8_STAGE(PG8_SA(0, 1), a2 + hstepA, voffA);
;             PG8_WAIT_V(8); PG8_WAIT_L(0); PG8_BAR; PG8_MMA(0, 0, At, B0); PG8_MMA(0, 1, At, B1); PG8_BAR; PG8_SCHED;
;             PG8_LDA(At, 1, 1); PG8_STAGE(PG8_SB(1, 0), b3, voffB); PG8_STAGE(PG8_SB(1, 1), b3 + hstepB, voffB); PG8_STAGE(PG8_SA(1, 0), a3, voffA);
;             PG8_WAIT_V(8); PG8_WAIT_L(0); PG8_BAR; PG8_MMA(1, 0, At, B0); PG8_MMA(1, 1, At, B1); PG8_BAR; PG8_SCHED;
	s_add_i32 s73, 0, 0x18000
	s_add_i32 s74, 0, 0x1c000
	v_add_u32_e32 v142, s73, v1
	v_add_u32_e32 v158, s74, v1
	ds_read_b128 v[130:133], v142
	ds_read_b128 v[134:137], v142 offset:1024
	ds_read_b128 v[138:141], v142 offset:2048
	ds_read_b128 v[142:145], v142 offset:3072
	ds_read_b128 v[146:149], v158
	ds_read_b128 v[150:153], v158 offset:1024
	ds_read_b128 v[154:157], v158 offset:2048
	ds_read_b128 v[158:161], v158 offset:3072
	s_add_u32 s34, s34, 0x100000
	s_addc_u32 s35, s35, 0
	s_mov_b32 m0, s49
	ds_read_b128 v[162:165], v207 offset:32768
	ds_read_b128 v[166:169], v207 offset:33792
	ds_read_b128 v[170:173], v207 offset:34816
	ds_read_b128 v[174:177], v207 offset:35840
	ds_read_b128 v[196:199], v207 offset:36864
	ds_read_b128 v[208:211], v207 offset:37888
	ds_read_b128 v[212:215], v207 offset:38912
	ds_read_b128 v[216:219], v207 offset:39936
	global_load_lds_dwordx4 v184, s[34:35]
	s_mov_b32 m0, s60
	s_nop 0
	global_load_lds_dwordx4 v180, s[34:35]
	s_waitcnt vmcnt(8)
	s_waitcnt lgkmcnt(0)
	s_barrier
	s_setprio 1
	s_waitcnt lgkmcnt(0)
	v_mfma_f32_16x16x32_bf16 v[122:125], v[130:133], v[162:165], v[122:125]
	v_mfma_f32_16x16x32_bf16 v[118:121], v[138:141], v[162:165], v[118:121]
	v_mfma_f32_16x16x32_bf16 v[106:109], v[130:133], v[170:173], v[106:109]
	v_mfma_f32_16x16x32_bf16 v[102:105], v[138:141], v[170:173], v[102:105]
	v_mfma_f32_16x16x32_bf16 v[90:93], v[130:133], v[196:199], v[90:93]
	v_mfma_f32_16x16x32_bf16 v[86:89], v[138:141], v[196:199], v[86:89]
	v_mfma_f32_16x16x32_bf16 v[74:77], v[130:133], v[212:215], v[74:77]
	v_mfma_f32_16x16x32_bf16 v[70:73], v[138:141], v[212:215], v[70:73]
	v_mfma_f32_16x16x32_bf16 v[122:125], v[134:137], v[166:169], v[122:125]
	v_mfma_f32_16x16x32_bf16 v[118:121], v[142:145], v[166:169], v[118:121]
	v_mfma_f32_16x16x32_bf16 v[106:109], v[134:137], v[174:177], v[106:109]
	v_mfma_f32_16x16x32_bf16 v[102:105], v[142:145], v[174:177], v[102:105]
	v_mfma_f32_16x16x32_bf16 v[90:93], v[134:137], v[208:211], v[90:93]
	v_mfma_f32_16x16x32_bf16 v[86:89], v[142:145], v[208:211], v[86:89]
	v_mfma_f32_16x16x32_bf16 v[74:77], v[134:137], v[216:219], v[74:77]
	v_mfma_f32_16x16x32_bf16 v[70:73], v[142:145], v[216:219], v[70:73]
	s_setprio 0
	s_setprio 1
	v_mfma_f32_16x16x32_bf16 v[126:129], v[146:149], v[162:165], v[126:129]
	v_mfma_f32_16x16x32_bf16 v[114:117], v[154:157], v[162:165], v[114:117]
	v_mfma_f32_16x16x32_bf16 v[110:113], v[146:149], v[170:173], v[110:113]
	v_mfma_f32_16x16x32_bf16 v[98:101], v[154:157], v[170:173], v[98:101]
	v_mfma_f32_16x16x32_bf16 v[94:97], v[146:149], v[196:199], v[94:97]
	v_mfma_f32_16x16x32_bf16 v[82:85], v[154:157], v[196:199], v[82:85]
	v_mfma_f32_16x16x32_bf16 v[78:81], v[146:149], v[212:215], v[78:81]
	v_mfma_f32_16x16x32_bf16 v[66:69], v[154:157], v[212:215], v[66:69]
	v_mfma_f32_16x16x32_bf16 v[126:129], v[150:153], v[166:169], v[126:129]
	v_mfma_f32_16x16x32_bf16 v[114:117], v[158:161], v[166:169], v[114:117]
	v_mfma_f32_16x16x32_bf16 v[110:113], v[150:153], v[174:177], v[110:113]
	v_mfma_f32_16x16x32_bf16 v[98:101], v[158:161], v[174:177], v[98:101]
	v_mfma_f32_16x16x32_bf16 v[94:97], v[150:153], v[208:211], v[94:97]
	v_mfma_f32_16x16x32_bf16 v[82:85], v[158:161], v[208:211], v[82:85]
	v_mfma_f32_16x16x32_bf16 v[78:81], v[150:153], v[216:219], v[78:81]
	v_mfma_f32_16x16x32_bf16 v[66:69], v[158:161], v[216:219], v[66:69]
	s_setprio 0
	s_barrier
	s_add_i32 s34, s73, s17
	s_mov_b32 m0, s34
	ds_read_b128 v[162:165], v207 offset:49152
	ds_read_b128 v[166:169], v207 offset:50176
	ds_read_b128 v[170:173], v207 offset:51200
	ds_read_b128 v[174:177], v207 offset:52224
	ds_read_b128 v[196:199], v207 offset:53248
	ds_read_b128 v[208:211], v207 offset:54272
	ds_read_b128 v[212:215], v207 offset:55296
	ds_read_b128 v[216:219], v207 offset:56320
	global_load_lds_dwordx4 v182, s[98:99]
	s_add_i32 m0, s34, 0x2000
	s_add_u32 s34, s42, 0x100080
	s_addc_u32 s35, s43, 0
	s_add_i32 s42, s74, s17
	global_load_lds_dwordx4 v178, s[98:99]
	s_mov_b32 m0, s42
	s_nop 0
	global_load_lds_dwordx4 v182, s[34:35]
	s_add_i32 m0, s42, 0x2000
	s_nop 0
	global_load_lds_dwordx4 v178, s[34:35]
	s_mov_b32 m0, s64
	s_nop 0
	global_load_lds_dwordx4 v184, s[100:101]
	s_mov_b32 m0, s65
	s_nop 0
	global_load_lds_dwordx4 v180, s[100:101]
	s_waitcnt vmcnt(8)
	s_waitcnt lgkmcnt(0)
	s_barrier
	s_setprio 1
	s_waitcnt lgkmcnt(0)
	v_mfma_f32_16x16x32_bf16 v[58:61], v[130:133], v[162:165], v[58:61]
	v_mfma_f32_16x16x32_bf16 v[54:57], v[138:141], v[162:165], v[54:57]
	v_mfma_f32_16x16x32_bf16 v[42:45], v[130:133], v[170:173], v[42:45]
	v_mfma_f32_16x16x32_bf16 v[38:41], v[138:141], v[170:173], v[38:41]
	v_mfma_f32_16x16x32_bf16 v[26:29], v[130:133], v[196:199], v[26:29]
	v_mfma_f32_16x16x32_bf16 v[22:25], v[138:141], v[196:199], v[22:25]
	v_mfma_f32_16x16x32_bf16 v[10:13], v[130:133], v[212:215], v[10:13]
	v_mfma_f32_16x16x32_bf16 v[6:9], v[138:141], v[212:215], v[6:9]
	v_mfma_f32_16x16x32_bf16 v[58:61], v[134:137], v[166:169], v[58:61]
	v_mfma_f32_16x16x32_bf16 v[54:57], v[142:145], v[166:169], v[54:57]
	v_mfma_f32_16x16x32_bf16 v[42:45], v[134:137], v[174:177], v[42:45]
	v_mfma_f32_16x16x32_bf16 v[38:41], v[142:145], v[174:177], v[38:41]
	v_mfma_f32_16x16x32_bf16 v[26:29], v[134:137], v[208:211], v[26:29]
	v_mfma_f32_16x16x32_bf16 v[22:25], v[142:145], v[208:211], v[22:25]
	v_mfma_f32_16x16x32_bf16 v[10:13], v[134:137], v[216:219], v[10:13]
	v_mfma_f32_16x16x32_bf16 v[6:9], v[142:145], v[216:219], v[6:9]
	s_setprio 0
	s_setprio 1
	v_mfma_f32_16x16x32_bf16 v[62:65], v[146:149], v[162:165], v[62:65]
	v_mfma_f32_16x16x32_bf16 v[50:53], v[154:157], v[162:165], v[50:53]
	v_mfma_f32_16x16x32_bf16 v[46:49], v[146:149], v[170:173], v[46:49]
	v_mfma_f32_16x16x32_bf16 v[34:37], v[154:157], v[170:173], v[34:37]
	v_mfma_f32_16x16x32_bf16 v[30:33], v[146:149], v[196:199], v[30:33]
	v_mfma_f32_16x16x32_bf16 v[18:21], v[154:157], v[196:199], v[18:21]
	v_mfma_f32_16x16x32_bf16 v[14:17], v[146:149], v[212:215], v[14:17]
	v_mfma_f32_16x16x32_bf16 v[2:5], v[154:157], v[212:215], v[2:5]
	v_mfma_f32_16x16x32_bf16 v[62:65], v[150:153], v[166:169], v[62:65]
	v_mfma_f32_16x16x32_bf16 v[50:53], v[158:161], v[166:169], v[50:53]
	v_mfma_f32_16x16x32_bf16 v[46:49], v[150:153], v[174:177], v[46:49]
	v_mfma_f32_16x16x32_bf16 v[34:37], v[158:161], v[174:177], v[34:37]
	v_mfma_f32_16x16x32_bf16 v[30:33], v[150:153], v[208:211], v[30:33]
	v_mfma_f32_16x16x32_bf16 v[18:21], v[158:161], v[208:211], v[18:21]
	v_mfma_f32_16x16x32_bf16 v[14:17], v[150:153], v[216:219], v[14:17]
	v_mfma_f32_16x16x32_bf16 v[2:5], v[158:161], v[216:219], v[2:5]
	s_setprio 0
	s_barrier
	s_add_i32 s53, s53, 2
	s_add_u32 s40, s40, 0x100
	s_addc_u32 s41, s41, 0
	s_add_u32 s45, s45, 0x100
	s_addc_u32 s52, s52, 0
	s_cmp_gt_u32 s53, 61
	s_cbranch_scc0 .LBB0_1127
	s_and_b64 vcc, exec, s[14:15]
	s_cbranch_vccz .LBB0_1130
	s_barrier

; #define PG8_STAGE(bufoff, gbase, voff) do { _Pragma("unroll") for (int _i = 0; _i < 2; ++_i) \
;         __builtin_amdgcn_global_load_lds((const unsigned*)((const char*)(gbase) + (voff)[_i]), (PG8_LAS unsigned*)(lds + (bufoff) + ldsw + _i * 8192), 16, 0, 0); } while (0)
; #define PG8_LDA(dst, b, h) do { _Pragma("unroll") for (int m = 0; m < 4; ++m) _Pragma("unroll") for (int k = 0; k < 2; ++k) dst[m][k] = *(const PG8_LAS bf16x8*)(lds + PG8_SA(b, h) + aoff + m * 2048 + k * 1024); } while (0)
; #define PG8_LDB(dst, b, h) do { _Pragma("unroll") for (int n = 0; n < 2; ++n) _Pragma("unroll") for (int k = 0; k < 2; ++k) dst[n][k] = *(const PG8_LAS bf16x8*)(lds + PG8_SB(b, h) + boff + n * 2048 + k * 1024); } while (0)
; #define PG8_MMA(ai, bj, At, Bt) do { __builtin_amdgcn_s_setprio(1); _Pragma("unroll") for (int m = 0; m < 4; ++m) _Pragma("unroll") for (int n = 0; n < 2; ++n) _Pragma("unroll") for (int k = 0; k < 2; ++k) \
;         acc[ai][bj][m][n] = __builtin_amdgcn_mfma_f32_16x16x32_bf16(Bt[n][k], At[m][k], acc[ai][bj][m][n], 0, 0, 0); __builtin_amdgcn_s_setprio(0); } while (0)
; #define PG8_WAIT_V(n) asm volatile("s_waitcnt vmcnt(" #n ")" ::: "memory")
; #define PG8_WAIT_L(n) asm volatile("s_waitcnt lgkmcnt(" #n ")" ::: "memory")
; #define PG8_BAR __builtin_amdgcn_s_barrier()
; #define PG8_SCHED __builtin_amdgcn_sched_barrier(0)
; template <class Epi, class Sched, bool ALIGN_EPI = false, bool SP2 = false>
; __device__ __forceinline__ void gemm_phase(PG8_LAS unsigned char* lds, const Gemm g, const Sched& S, const Epi& E) {
;     ...
;             PG8_LDB(B0, 0, 0); PG8_LDB(B1, 0, 1); PG8_SCHED; PG8_LDA(At, 0, 0); PG8_STAGE(PG8_SA(1, 1), a1 + hstepA, voffA);
;             PG8_WAIT_V(8); PG8_WAIT_L(0); PG8_BAR; PG8_MMA(0, 0, At, B0); PG8_MMA(0, 1, At, B1); PG8_BAR; PG8_SCHED;
;             PG8_LDA(At, 0, 1); PG8_STAGE(PG8_SB(0, 0), b2, voffB); PG8_STAGE(PG8_SB(0, 1), b2 + hstepB, voffB); PG8_STAGE(PG8_SA(0, 0), a2, voffA);
;             PG8_WAIT_V(8); PG8_WAIT_L(0); PG8_BAR; PG8_MMA(1, 0, At, B0); PG8_MMA(1, 1, At, B1); PG8_BAR; PG8_SCHED;
.LBB0_1206:
	ds_read_b128 v[130:133], v166
	ds_read_b128 v[134:137], v166 offset:1024
	ds_read_b128 v[138:141], v166 offset:2048
	ds_read_b128 v[142:145], v166 offset:3072
	ds_read_b128 v[170:173], v167
	ds_read_b128 v[174:177], v167 offset:1024
	ds_read_b128 v[178:181], v167 offset:2048
	ds_read_b128 v[182:185], v167 offset:3072
	s_add_u32 s36, s24, 0x100
	s_addc_u32 s37, s25, 0
	s_cmpk_eq_i32 s64, 0xbc
	s_cselect_b32 s35, s7, s37
	s_cselect_b32 s34, s6, s36
	s_cselect_b32 s39, s23, s63
	s_cselect_b32 s38, s22, s62
	s_add_i32 m0, s27, 0xc000
	ds_read_b128 v[186:189], v168
	ds_read_b128 v[190:193], v168 offset:1024
	ds_read_b128 v[194:197], v168 offset:2048
	ds_read_b128 v[198:201], v168 offset:3072
	ds_read_b128 v[202:205], v168 offset:4096
	ds_read_b128 v[206:209], v168 offset:5120
	ds_read_b128 v[210:213], v168 offset:6144
	ds_read_b128 v[214:217], v168 offset:7168
	global_load_lds_dwordx4 v154, s[24:25]
	s_add_i32 m0, s27, 0xe000
	s_nop 0
	global_load_lds_dwordx4 v156, s[24:25]
	s_waitcnt vmcnt(8)
	s_waitcnt lgkmcnt(0)
	s_barrier
	s_setprio 1
	s_waitcnt lgkmcnt(0)
	v_mfma_f32_16x16x32_bf16 v[126:129], v[130:133], v[186:189], v[126:129]
	v_mfma_f32_16x16x32_bf16 v[122:125], v[138:141], v[186:189], v[122:125]
	v_mfma_f32_16x16x32_bf16 v[118:121], v[130:133], v[194:197], v[118:121]
	v_mfma_f32_16x16x32_bf16 v[114:117], v[138:141], v[194:197], v[114:117]
	v_mfma_f32_16x16x32_bf16 v[110:113], v[130:133], v[202:205], v[110:113]
	v_mfma_f32_16x16x32_bf16 v[102:105], v[138:141], v[202:205], v[102:105]
	v_mfma_f32_16x16x32_bf16 v[94:97], v[130:133], v[210:213], v[94:97]
	v_mfma_f32_16x16x32_bf16 v[86:89], v[138:141], v[210:213], v[86:89]
	v_mfma_f32_16x16x32_bf16 v[126:129], v[134:137], v[190:193], v[126:129]
	v_mfma_f32_16x16x32_bf16 v[122:125], v[142:145], v[190:193], v[122:125]
	v_mfma_f32_16x16x32_bf16 v[118:121], v[134:137], v[198:201], v[118:121]
	v_mfma_f32_16x16x32_bf16 v[114:117], v[142:145], v[198:201], v[114:117]
	v_mfma_f32_16x16x32_bf16 v[110:113], v[134:137], v[206:209], v[110:113]
	v_mfma_f32_16x16x32_bf16 v[102:105], v[142:145], v[206:209], v[102:105]
	v_mfma_f32_16x16x32_bf16 v[94:97], v[134:137], v[214:217], v[94:97]
	v_mfma_f32_16x16x32_bf16 v[86:89], v[142:145], v[214:217], v[86:89]
	s_setprio 0
	s_setprio 1
	v_mfma_f32_16x16x32_bf16 v[106:109], v[170:173], v[186:189], v[106:109]
	v_mfma_f32_16x16x32_bf16 v[98:101], v[178:181], v[186:189], v[98:101]
	v_mfma_f32_16x16x32_bf16 v[90:93], v[170:173], v[194:197], v[90:93]
	v_mfma_f32_16x16x32_bf16 v[82:85], v[178:181], v[194:197], v[82:85]
	v_mfma_f32_16x16x32_bf16 v[78:81], v[170:173], v[202:205], v[78:81]
	v_mfma_f32_16x16x32_bf16 v[74:77], v[178:181], v[202:205], v[74:77]
	v_mfma_f32_16x16x32_bf16 v[70:73], v[170:173], v[210:213], v[70:73]
	v_mfma_f32_16x16x32_bf16 v[66:69], v[178:181], v[210:213], v[66:69]
	v_mfma_f32_16x16x32_bf16 v[106:109], v[174:177], v[190:193], v[106:109]
	v_mfma_f32_16x16x32_bf16 v[98:101], v[182:185], v[190:193], v[98:101]
	v_mfma_f32_16x16x32_bf16 v[90:93], v[174:177], v[198:201], v[90:93]
	v_mfma_f32_16x16x32_bf16 v[82:85], v[182:185], v[198:201], v[82:85]
	v_mfma_f32_16x16x32_bf16 v[78:81], v[174:177], v[206:209], v[78:81]
	v_mfma_f32_16x16x32_bf16 v[74:77], v[182:185], v[206:209], v[74:77]
	v_mfma_f32_16x16x32_bf16 v[70:73], v[174:177], v[214:217], v[70:73]
	v_mfma_f32_16x16x32_bf16 v[66:69], v[182:185], v[214:217], v[66:69]
	s_setprio 0
	s_barrier
	s_add_i32 s24, s48, s26
	s_add_u32 s98, s38, 0x80
	s_addc_u32 s99, s39, 0
	s_add_u32 s100, s34, 0x80
	s_addc_u32 s101, s35, 0
	s_mov_b32 m0, s24
	ds_read_b128 v[186:189], v168 offset:16384
	ds_read_b128 v[190:193], v168 offset:17408
	ds_read_b128 v[194:197], v168 offset:18432
	ds_read_b128 v[198:201], v168 offset:19456
	ds_read_b128 v[202:205], v168 offset:20480
	ds_read_b128 v[206:209], v168 offset:21504
	ds_read_b128 v[210:213], v168 offset:22528
	ds_read_b128 v[214:217], v168 offset:23552
	global_load_lds_dwordx4 v150, s[38:39]
	s_add_i32 m0, s24, 0x2000
	s_add_u32 s24, s38, 0x300000
	s_addc_u32 s25, s39, 0
	s_add_i32 s65, s49, s26
	global_load_lds_dwordx4 v146, s[38:39]
	s_mov_b32 m0, s65
	s_nop 0
	global_load_lds_dwordx4 v150, s[24:25]
	s_add_i32 m0, s65, 0x2000
	s_nop 0
	global_load_lds_dwordx4 v146, s[24:25]
	s_mov_b32 m0, s27
	s_nop 0
	global_load_lds_dwordx4 v152, s[34:35]
	s_mov_b32 m0, s40
	s_nop 0
	global_load_lds_dwordx4 v148, s[34:35]
	s_waitcnt vmcnt(8)
	s_waitcnt lgkmcnt(0)
	s_barrier
	s_setprio 1
	s_waitcnt lgkmcnt(0)
	v_mfma_f32_16x16x32_bf16 v[62:65], v[130:133], v[186:189], v[62:65]
	v_mfma_f32_16x16x32_bf16 v[58:61], v[138:141], v[186:189], v[58:61]
	v_mfma_f32_16x16x32_bf16 v[50:53], v[130:133], v[194:197], v[50:53]
	v_mfma_f32_16x16x32_bf16 v[42:45], v[138:141], v[194:197], v[42:45]
	v_mfma_f32_16x16x32_bf16 v[34:37], v[130:133], v[202:205], v[34:37]
	v_mfma_f32_16x16x32_bf16 v[26:29], v[138:141], v[202:205], v[26:29]
	v_mfma_f32_16x16x32_bf16 v[18:21], v[130:133], v[210:213], v[18:21]
	v_mfma_f32_16x16x32_bf16 v[10:13], v[138:141], v[210:213], v[10:13]
	v_mfma_f32_16x16x32_bf16 v[62:65], v[134:137], v[190:193], v[62:65]
	v_mfma_f32_16x16x32_bf16 v[58:61], v[142:145], v[190:193], v[58:61]
	v_mfma_f32_16x16x32_bf16 v[50:53], v[134:137], v[198:201], v[50:53]
	v_mfma_f32_16x16x32_bf16 v[42:45], v[142:145], v[198:201], v[42:45]
	v_mfma_f32_16x16x32_bf16 v[34:37], v[134:137], v[206:209], v[34:37]
	v_mfma_f32_16x16x32_bf16 v[26:29], v[142:145], v[206:209], v[26:29]
	v_mfma_f32_16x16x32_bf16 v[18:21], v[134:137], v[214:217], v[18:21]
	v_mfma_f32_16x16x32_bf16 v[10:13], v[142:145], v[214:217], v[10:13]
	s_setprio 0
	s_setprio 1
	v_mfma_f32_16x16x32_bf16 v[54:57], v[170:173], v[186:189], v[54:57]
	v_mfma_f32_16x16x32_bf16 v[46:49], v[178:181], v[186:189], v[46:49]
	v_mfma_f32_16x16x32_bf16 v[38:41], v[170:173], v[194:197], v[38:41]
	v_mfma_f32_16x16x32_bf16 v[30:33], v[178:181], v[194:197], v[30:33]
	v_mfma_f32_16x16x32_bf16 v[22:25], v[170:173], v[202:205], v[22:25]
	v_mfma_f32_16x16x32_bf16 v[14:17], v[178:181], v[202:205], v[14:17]
	v_mfma_f32_16x16x32_bf16 v[6:9], v[170:173], v[210:213], v[6:9]
	v_mfma_f32_16x16x32_bf16 v[2:5], v[178:181], v[210:213], v[2:5]
	v_mfma_f32_16x16x32_bf16 v[54:57], v[174:177], v[190:193], v[54:57]
	v_mfma_f32_16x16x32_bf16 v[46:49], v[182:185], v[190:193], v[46:49]
	v_mfma_f32_16x16x32_bf16 v[38:41], v[174:177], v[198:201], v[38:41]
	v_mfma_f32_16x16x32_bf16 v[30:33], v[182:185], v[198:201], v[30:33]
	v_mfma_f32_16x16x32_bf16 v[22:25], v[174:177], v[206:209], v[22:25]
	v_mfma_f32_16x16x32_bf16 v[14:17], v[182:185], v[206:209], v[14:17]
	v_mfma_f32_16x16x32_bf16 v[6:9], v[174:177], v[214:217], v[6:9]
	v_mfma_f32_16x16x32_bf16 v[2:5], v[182:185], v[214:217], v[2:5]
	s_setprio 0
	s_barrier
; #define PG8_STAGE(bufoff, gbase, voff) do { _Pragma("unroll") for (int _i = 0; _i < 2; ++_i) \
;         __builtin_amdgcn_global_load_lds((const unsigned*)((const char*)(gbase) + (voff)[_i]), (PG8_LAS unsigned*)(lds + (bufoff) + ldsw + _i * 8192), 16, 0, 0); } while (0)
; #define PG8_LDA(dst, b, h) do { _Pragma("unroll") for (int m = 0; m < 4; ++m) _Pragma("unroll") for (int k = 0; k < 2; ++k) dst[m][k] = *(const PG8_LAS bf16x8*)(lds + PG8_SA(b, h) + aoff + m * 2048 + k * 1024); } while (0)
; #define PG8_LDB(dst, b, h) do { _Pragma("unroll") for (int n = 0; n < 2; ++n) _Pragma("unroll") for (int k = 0; k < 2; ++k) dst[n][k] = *(const PG8_LAS bf16x8*)(lds + PG8_SB(b, h) + boff + n * 2048 + k * 1024); } while (0)
; #define PG8_MMA(ai, bj, At, Bt) do { __builtin_amdgcn_s_setprio(1); _Pragma("unroll") for (int m = 0; m < 4; ++m) _Pragma("unroll") for (int n = 0; n < 2; ++n) _Pragma("unroll") for (int k = 0; k < 2; ++k) \
;         acc[ai][bj][m][n] = __builtin_amdgcn_mfma_f32_16x16x32_bf16(Bt[n][k], At[m][k], acc[ai][bj][m][n], 0, 0, 0); __builtin_amdgcn_s_setprio(0); } while (0)
; #define PG8_WAIT_V(n) asm volatile("s_waitcnt vmcnt(" #n ")" ::: "memory")
; #define PG8_WAIT_L(n) asm volatile("s_waitcnt lgkmcnt(" #n ")" ::: "memory")
; #define PG8_BAR __builtin_amdgcn_s_barrier()
; #define PG8_SCHED __builtin_amdgcn_sched_barrier(0)
; template <class Epi, class Sched, bool ALIGN_EPI = false, bool SP2 = false>
; __device__ __forceinline__ void gemm_phase(PG8_LAS unsigned char* lds, const Gemm g, const Sched& S, const Epi& E) {
;     ...
;             PG8_LDB(B0, 1, 0); PG8_LDB(B1, 1, 1); PG8_SCHED; PG8_LDA(At, 1, 0); PG8_STAGE(PG8_SA(0, 1), a2 + hstepA, voffA);
;             PG8_WAIT_V(8); PG8_WAIT_L(0); PG8_BAR; PG8_MMA(0, 0, At, B0); PG8_MMA(0, 1, At, B1); PG8_BAR; PG8_SCHED;
;             PG8_LDA(At, 1, 1); PG8_STAGE(PG8_SB(1, 0), b3, voffB); PG8_STAGE(PG8_SB(1, 1), b3 + hstepB, voffB); PG8_STAGE(PG8_SA(1, 0), a3, voffA);
;             PG8_WAIT_V(8); PG8_WAIT_L(0); PG8_BAR; PG8_MMA(1, 0, At, B0); PG8_MMA(1, 1, At, B1); PG8_BAR; PG8_SCHED;
	s_add_i32 s65, 0, 0x18000
	s_add_i32 s66, 0, 0x1c000
	v_add_u32_e32 v142, s65, v164
	v_add_u32_e32 v169, s66, v164
	ds_read_b128 v[130:133], v142
	ds_read_b128 v[134:137], v142 offset:1024
	ds_read_b128 v[138:141], v142 offset:2048
	ds_read_b128 v[142:145], v142 offset:3072
	ds_read_b128 v[170:173], v169
	ds_read_b128 v[174:177], v169 offset:1024
	ds_read_b128 v[178:181], v169 offset:2048
	ds_read_b128 v[182:185], v169 offset:3072
	s_add_u32 s24, s34, 0x300000
	s_addc_u32 s25, s35, 0
	s_mov_b32 m0, s41
	ds_read_b128 v[186:189], v168 offset:32768
	ds_read_b128 v[190:193], v168 offset:33792
	ds_read_b128 v[194:197], v168 offset:34816
	ds_read_b128 v[198:201], v168 offset:35840
	ds_read_b128 v[202:205], v168 offset:36864
	ds_read_b128 v[206:209], v168 offset:37888
	ds_read_b128 v[210:213], v168 offset:38912
	ds_read_b128 v[214:217], v168 offset:39936
	global_load_lds_dwordx4 v152, s[24:25]
	s_mov_b32 m0, s42
	s_nop 0
	global_load_lds_dwordx4 v148, s[24:25]
	s_waitcnt vmcnt(8)
	s_waitcnt lgkmcnt(0)
	s_barrier
	s_setprio 1
	s_waitcnt lgkmcnt(0)
	v_mfma_f32_16x16x32_bf16 v[126:129], v[130:133], v[186:189], v[126:129]
	v_mfma_f32_16x16x32_bf16 v[122:125], v[138:141], v[186:189], v[122:125]
	v_mfma_f32_16x16x32_bf16 v[118:121], v[130:133], v[194:197], v[118:121]
	v_mfma_f32_16x16x32_bf16 v[114:117], v[138:141], v[194:197], v[114:117]
	v_mfma_f32_16x16x32_bf16 v[110:113], v[130:133], v[202:205], v[110:113]
	v_mfma_f32_16x16x32_bf16 v[102:105], v[138:141], v[202:205], v[102:105]
	v_mfma_f32_16x16x32_bf16 v[94:97], v[130:133], v[210:213], v[94:97]
	v_mfma_f32_16x16x32_bf16 v[86:89], v[138:141], v[210:213], v[86:89]
	v_mfma_f32_16x16x32_bf16 v[126:129], v[134:137], v[190:193], v[126:129]
	v_mfma_f32_16x16x32_bf16 v[122:125], v[142:145], v[190:193], v[122:125]
	v_mfma_f32_16x16x32_bf16 v[118:121], v[134:137], v[198:201], v[118:121]
	v_mfma_f32_16x16x32_bf16 v[114:117], v[142:145], v[198:201], v[114:117]
	v_mfma_f32_16x16x32_bf16 v[110:113], v[134:137], v[206:209], v[110:113]
	v_mfma_f32_16x16x32_bf16 v[102:105], v[142:145], v[206:209], v[102:105]
	v_mfma_f32_16x16x32_bf16 v[94:97], v[134:137], v[214:217], v[94:97]
	v_mfma_f32_16x16x32_bf16 v[86:89], v[142:145], v[214:217], v[86:89]
	s_setprio 0
	s_setprio 1
	v_mfma_f32_16x16x32_bf16 v[106:109], v[170:173], v[186:189], v[106:109]
	v_mfma_f32_16x16x32_bf16 v[98:101], v[178:181], v[186:189], v[98:101]
	v_mfma_f32_16x16x32_bf16 v[90:93], v[170:173], v[194:197], v[90:93]
	v_mfma_f32_16x16x32_bf16 v[82:85], v[178:181], v[194:197], v[82:85]
	v_mfma_f32_16x16x32_bf16 v[78:81], v[170:173], v[202:205], v[78:81]
	v_mfma_f32_16x16x32_bf16 v[74:77], v[178:181], v[202:205], v[74:77]
	v_mfma_f32_16x16x32_bf16 v[70:73], v[170:173], v[210:213], v[70:73]
	v_mfma_f32_16x16x32_bf16 v[66:69], v[178:181], v[210:213], v[66:69]
	v_mfma_f32_16x16x32_bf16 v[106:109], v[174:177], v[190:193], v[106:109]
	v_mfma_f32_16x16x32_bf16 v[98:101], v[182:185], v[190:193], v[98:101]
	v_mfma_f32_16x16x32_bf16 v[90:93], v[174:177], v[198:201], v[90:93]
	v_mfma_f32_16x16x32_bf16 v[82:85], v[182:185], v[198:201], v[82:85]
	v_mfma_f32_16x16x32_bf16 v[78:81], v[174:177], v[206:209], v[78:81]
	v_mfma_f32_16x16x32_bf16 v[74:77], v[182:185], v[206:209], v[74:77]
	v_mfma_f32_16x16x32_bf16 v[70:73], v[174:177], v[214:217], v[70:73]
	v_mfma_f32_16x16x32_bf16 v[66:69], v[182:185], v[214:217], v[66:69]
	s_setprio 0
	s_barrier
	s_add_i32 s24, s65, s26
	s_mov_b32 m0, s24
	ds_read_b128 v[186:189], v168 offset:49152
	ds_read_b128 v[190:193], v168 offset:50176
	ds_read_b128 v[194:197], v168 offset:51200
	ds_read_b128 v[198:201], v168 offset:52224
	ds_read_b128 v[202:205], v168 offset:53248
	ds_read_b128 v[206:209], v168 offset:54272
	ds_read_b128 v[210:213], v168 offset:55296
	ds_read_b128 v[214:217], v168 offset:56320
	global_load_lds_dwordx4 v150, s[98:99]
	s_add_i32 m0, s24, 0x2000
	s_add_u32 s24, s38, 0x300080
	s_addc_u32 s25, s39, 0
	s_add_i32 s34, s66, s26
	global_load_lds_dwordx4 v146, s[98:99]
	s_mov_b32 m0, s34
	s_nop 0
	global_load_lds_dwordx4 v150, s[24:25]
	s_add_i32 m0, s34, 0x2000
	s_nop 0
	global_load_lds_dwordx4 v146, s[24:25]
	s_mov_b32 m0, s46
	s_nop 0
	global_load_lds_dwordx4 v152, s[100:101]
	s_mov_b32 m0, s47
	s_nop 0
	global_load_lds_dwordx4 v148, s[100:101]
	s_waitcnt vmcnt(8)
	s_waitcnt lgkmcnt(0)
	s_barrier
	s_setprio 1
	s_waitcnt lgkmcnt(0)
	v_mfma_f32_16x16x32_bf16 v[62:65], v[130:133], v[186:189], v[62:65]
	v_mfma_f32_16x16x32_bf16 v[58:61], v[138:141], v[186:189], v[58:61]
	v_mfma_f32_16x16x32_bf16 v[50:53], v[130:133], v[194:197], v[50:53]
	v_mfma_f32_16x16x32_bf16 v[42:45], v[138:141], v[194:197], v[42:45]
	v_mfma_f32_16x16x32_bf16 v[34:37], v[130:133], v[202:205], v[34:37]
	v_mfma_f32_16x16x32_bf16 v[26:29], v[138:141], v[202:205], v[26:29]
	v_mfma_f32_16x16x32_bf16 v[18:21], v[130:133], v[210:213], v[18:21]
	v_mfma_f32_16x16x32_bf16 v[10:13], v[138:141], v[210:213], v[10:13]
	v_mfma_f32_16x16x32_bf16 v[62:65], v[134:137], v[190:193], v[62:65]
	v_mfma_f32_16x16x32_bf16 v[58:61], v[142:145], v[190:193], v[58:61]
	v_mfma_f32_16x16x32_bf16 v[50:53], v[134:137], v[198:201], v[50:53]
	v_mfma_f32_16x16x32_bf16 v[42:45], v[142:145], v[198:201], v[42:45]
	v_mfma_f32_16x16x32_bf16 v[34:37], v[134:137], v[206:209], v[34:37]
	v_mfma_f32_16x16x32_bf16 v[26:29], v[142:145], v[206:209], v[26:29]
	v_mfma_f32_16x16x32_bf16 v[18:21], v[134:137], v[214:217], v[18:21]
	v_mfma_f32_16x16x32_bf16 v[10:13], v[142:145], v[214:217], v[10:13]
	s_setprio 0
	s_setprio 1
	v_mfma_f32_16x16x32_bf16 v[54:57], v[170:173], v[186:189], v[54:57]
	v_mfma_f32_16x16x32_bf16 v[46:49], v[178:181], v[186:189], v[46:49]
	v_mfma_f32_16x16x32_bf16 v[38:41], v[170:173], v[194:197], v[38:41]
	v_mfma_f32_16x16x32_bf16 v[30:33], v[178:181], v[194:197], v[30:33]
	v_mfma_f32_16x16x32_bf16 v[22:25], v[170:173], v[202:205], v[22:25]
	v_mfma_f32_16x16x32_bf16 v[14:17], v[178:181], v[202:205], v[14:17]
	v_mfma_f32_16x16x32_bf16 v[6:9], v[170:173], v[210:213], v[6:9]
	v_mfma_f32_16x16x32_bf16 v[2:5], v[178:181], v[210:213], v[2:5]
	v_mfma_f32_16x16x32_bf16 v[54:57], v[174:177], v[190:193], v[54:57]
	v_mfma_f32_16x16x32_bf16 v[46:49], v[182:185], v[190:193], v[46:49]
	v_mfma_f32_16x16x32_bf16 v[38:41], v[174:177], v[198:201], v[38:41]
	v_mfma_f32_16x16x32_bf16 v[30:33], v[182:185], v[198:201], v[30:33]
	v_mfma_f32_16x16x32_bf16 v[22:25], v[174:177], v[206:209], v[22:25]
	v_mfma_f32_16x16x32_bf16 v[14:17], v[182:185], v[206:209], v[14:17]
	v_mfma_f32_16x16x32_bf16 v[6:9], v[174:177], v[214:217], v[6:9]
	v_mfma_f32_16x16x32_bf16 v[2:5], v[182:185], v[214:217], v[2:5]
	s_setprio 0
	s_barrier
	s_add_i32 s64, s64, 2
	s_add_u32 s62, s62, 0x100
	s_addc_u32 s63, s63, 0
	s_cmpk_gt_u32 s64, 0xbd
	s_mov_b64 s[24:25], s[36:37]
	s_cbranch_scc0 .LBB0_1206
	s_and_b64 vcc, exec, s[12:13]
	s_cbranch_vccz .LBB0_1209
	s_barrier

; __global__ void __launch_bounds__(NTHREADS, 2) fwd(Args a) {
	.amdhsa_kernel _Z3fwd4Args
		.amdhsa_group_segment_fixed_size 0
		.amdhsa_private_segment_fixed_size 0
		.amdhsa_kernarg_size 496
		.amdhsa_user_sgpr_count 2
		.amdhsa_user_sgpr_dispatch_ptr 0
		.amdhsa_user_sgpr_queue_ptr 0
		.amdhsa_user_sgpr_kernarg_segment_ptr 1
		.amdhsa_user_sgpr_dispatch_id 0
		.amdhsa_user_sgpr_kernarg_preload_length 0
		.amdhsa_user_sgpr_kernarg_preload_offset 0
		.amdhsa_user_sgpr_private_segment_size 0
		.amdhsa_uses_dynamic_stack 0
		.amdhsa_enable_private_segment 0
		.amdhsa_system_sgpr_workgroup_id_x 1
		.amdhsa_system_sgpr_workgroup_id_y 0
		.amdhsa_system_sgpr_workgroup_id_z 0
		.amdhsa_system_sgpr_workgroup_info 0
		.amdhsa_system_vgpr_workitem_id 0
		.amdhsa_next_free_vgpr 255
		.amdhsa_next_free_sgpr 102
		.amdhsa_accum_offset 256
		.amdhsa_reserve_vcc 1
		.amdhsa_float_round_mode_32 0
		.amdhsa_float_round_mode_16_64 0
		.amdhsa_float_denorm_mode_32 3
		.amdhsa_float_denorm_mode_16_64 3
		.amdhsa_dx10_clamp 1
		.amdhsa_ieee_mode 1
		.amdhsa_fp16_overflow 0
		.amdhsa_tg_split 0
		.amdhsa_exception_fp_ieee_invalid_op 0
		.amdhsa_exception_fp_denorm_src 0
		.amdhsa_exception_fp_ieee_div_zero 0
		.amdhsa_exception_fp_ieee_overflow 0
		.amdhsa_exception_fp_ieee_underflow 0
		.amdhsa_exception_fp_ieee_inexact 0
		.amdhsa_exception_int_div_zero 0
	.end_amdhsa_kernel

; __global__ void __launch_bounds__(NTHREADS, 2) fwd(Args a) {
.Lfunc_end0:
	.size	_Z3fwd4Args, .Lfunc_end0-_Z3fwd4Args
	.set _Z3fwd4Args.num_vgpr, 255
	.set _Z3fwd4Args.num_agpr, 0
	.set _Z3fwd4Args.numbered_sgpr, 102
	.set _Z3fwd4Args.num_named_barrier, 0
	.set _Z3fwd4Args.private_seg_size, 0
	.set _Z3fwd4Args.uses_vcc, 1
	.set _Z3fwd4Args.uses_flat_scratch, 0
	.set _Z3fwd4Args.has_dyn_sized_stack, 0
	.set _Z3fwd4Args.has_recursion, 0
	.set _Z3fwd4Args.has_indirect_call, 0

; __global__ void __launch_bounds__(NTHREADS, 2) fwd(Args a) {
amdhsa.kernels:
  - .agpr_count:     0
    .args:
      - .offset:         0
        .size:           240
        .value_kind:     by_value
      - .offset:         240
        .size:           4
        .value_kind:     hidden_block_count_x
      - .offset:         244
        .size:           4
        .value_kind:     hidden_block_count_y
      - .offset:         248
        .size:           4
        .value_kind:     hidden_block_count_z
      - .offset:         252
        .size:           2
        .value_kind:     hidden_group_size_x
      - .offset:         254
        .size:           2
        .value_kind:     hidden_group_size_y
      - .offset:         256
        .size:           2
        .value_kind:     hidden_group_size_z
      - .offset:         258
        .size:           2
        .value_kind:     hidden_remainder_x
      - .offset:         260
        .size:           2
        .value_kind:     hidden_remainder_y
      - .offset:         262
        .size:           2
        .value_kind:     hidden_remainder_z
      - .offset:         280
        .size:           8
        .value_kind:     hidden_global_offset_x
      - .offset:         288
        .size:           8
        .value_kind:     hidden_global_offset_y
      - .offset:         296
        .size:           8
        .value_kind:     hidden_global_offset_z
      - .offset:         304
        .size:           2
        .value_kind:     hidden_grid_dims
      - .offset:         360
        .size:           4
        .value_kind:     hidden_dynamic_lds_size
    .group_segment_fixed_size: 0
    .kernarg_segment_align: 8
    .kernarg_segment_size: 496
    .language:       OpenCL C
    .language_version:
      - 2
      - 0
    .max_flat_workgroup_size: 512
    .name:           _Z3fwd4Args
    .private_segment_fixed_size: 0
    .sgpr_count:     108
    .sgpr_spill_count: 64
    .symbol:         _Z3fwd4Args.kd
    .uniform_work_group_size: 1
    .uses_dynamic_stack: false
    .vgpr_count:     255
    .vgpr_spill_count: 0
    .wavefront_size: 64
